# v61 + gla operand-prefetch address strength reduction + removal of no-op lgkmcnt waits left in the DPP-converted LayerNorm loops
# speedup vs baseline: 1.0053x; 1.0053x over previous
; __device__ __forceinline__ unsigned pk2(float lo, float hi) { unsigned r; asm("v_cvt_pk_bf16_f32 %0, %1, %2" : "=v"(r) : "v"(lo), "v"(hi)); return r; }
; __device__ __forceinline__ void ln_panel(const float* src, float* dst, bf16_t* dstb, const float* gam, const float* bet, LAS f32x2* T) {
;     ...
;     for (int it = 0; it < 32 / NB; ++it) {
;         const int r = r0 + it * NB;
;         if (it + 1 < 32 / NB) {
; #pragma unroll
;             for (int b = 0; b < NB; ++b)
; #pragma unroll
;                 for (int j = 0; j < 4; ++j) nxt[b][j] = ((const f32x4*)(src + (size_t)(r + NB + b) * DM))[lane + 64 * j];
;         }
;         float s[NB], s2[NB];
; #pragma unroll
;         for (int b = 0; b < NB; ++b) { s[b] = 0.f;
; #pragma unroll
;             for (int j = 0; j < 4; ++j) s[b] += (cur[b][j].x + cur[b][j].y) + (cur[b][j].z + cur[b][j].w); }
; #pragma unroll
;         for (int o = 1; o < 64; o <<= 1)
; #pragma unroll
;             for (int b = 0; b < NB; ++b) s[b] += __shfl_xor(s[b], o);
; #pragma unroll
;         for (int b = 0; b < NB; ++b) { const float mean = s[b] * (1.f / DM); s2[b] = 0.f;
; #pragma unroll
;             for (int j = 0; j < 4; ++j) { cur[b][j] = cur[b][j] - mean; s2[b] += (cur[b][j].x * cur[b][j].x + cur[b][j].y * cur[b][j].y) + (cur[b][j].z * cur[b][j].z + cur[b][j].w * cur[b][j].w); } }
; #pragma unroll
;         for (int o = 1; o < 64; o <<= 1)
; #pragma unroll
;             for (int b = 0; b < NB; ++b) s2[b] += __shfl_xor(s2[b], o);
; #pragma unroll
;         for (int b = 0; b < NB; ++b) {
;             const float rstd = 1.f / sqrtf(s2[b] * (1.f / DM) + LN_EPS);
;             if (T && lane == 0) T[r + b] = (f32x2){s[b] * (1.f / DM), rstd};
; #pragma unroll
;             for (int j = 0; j < 4; ++j) {
;                 const f32x4 o = cur[b][j] * rstd * gv[j] + bv[j];
;                 if (dst) ((f32x4*)(dst + (size_t)(r + b) * DM))[lane + 64 * j] = o;
;                 if (dstb) { u32x2 w; w.x = pk2(o.x, o.y); w.y = pk2(o.z, o.w); ((u32x2*)(dstb + (size_t)(r + b) * DM))[lane + 64 * j] = w; }
;             }
;         }
; #pragma unroll
;         for (int b = 0; b < NB; ++b)
; #pragma unroll
;             for (int j = 0; j < 4; ++j) cur[b][j] = nxt[b][j];
;     }
.LBB0_107:
	v_lshl_add_u64 v[66:67], v[102:103], 0, s[12:13]
	s_waitcnt vmcnt(15)
	v_mov_b32_e32 v68, v35
	v_mov_b32_e32 v69, v36
	v_mov_b32_e32 v70, v34
	v_mov_b32_e32 v71, v37
	s_waitcnt vmcnt(14)
	v_mov_b32_e32 v72, v39
	v_mov_b32_e32 v73, v40
	v_mov_b32_e32 v74, v38
	v_mov_b32_e32 v75, v41
	v_add_co_u32_e32 v110, vcc, 0x2000, v66
	s_waitcnt vmcnt(11)
	v_mov_b32_e32 v80, v51
	v_mov_b32_e32 v81, v52
	v_mov_b32_e32 v82, v50
	v_mov_b32_e32 v83, v53
	s_waitcnt vmcnt(10)
	v_mov_b32_e32 v84, v55
	v_mov_b32_e32 v85, v56
	v_mov_b32_e32 v86, v54
	v_mov_b32_e32 v87, v57
	v_pk_add_f32 v[68:69], v[68:69], v[70:71]
	v_pk_add_f32 v[70:71], v[72:73], v[74:75]
	v_addc_co_u32_e32 v111, vcc, 0, v67, vcc
	v_pk_add_f32 v[72:73], v[80:81], v[82:83]
	v_pk_add_f32 v[74:75], v[84:85], v[86:87]
	v_add_co_u32_e32 v116, vcc, 0x3000, v66
	v_add_f32_e32 v66, v68, v69
	v_pk_add_f32 v[118:119], v[70:71], v[70:71] op_sel:[0,1] op_sel_hi:[1,0]
	v_add_f32_e32 v76, v42, v43
	v_add_f32_e32 v78, v44, v45
	v_mov_b32_e32 v105, v46
	v_mov_b32_e32 v77, v48
	v_mov_b32_e32 v79, v49
	v_add_f32_e32 v68, v72, v73
	v_pk_add_f32 v[120:121], v[74:75], v[74:75] op_sel:[0,1] op_sel_hi:[1,0]
	v_add_f32_e32 v104, 0, v66
	v_mov_b32_e32 v119, v47
	s_waitcnt vmcnt(9)
	v_add_f32_e32 v88, v58, v59
	v_add_f32_e32 v90, v60, v61
	s_waitcnt vmcnt(8)
	v_mov_b32_e32 v107, v62
	v_mov_b32_e32 v89, v64
	v_mov_b32_e32 v91, v65
	v_pk_add_f32 v[112:113], v[76:77], v[78:79]
	v_add_f32_e32 v106, 0, v68
	v_mov_b32_e32 v121, v63
	v_pk_add_f32 v[104:105], v[104:105], v[118:119]
	v_pk_add_f32 v[114:115], v[88:89], v[90:91]
	v_pk_add_f32 v[106:107], v[106:107], v[120:121]
	v_pk_add_f32 v[104:105], v[104:105], v[112:113]
	v_pk_add_f32 v[106:107], v[106:107], v[114:115]
	v_add_f32_e32 v104, v104, v105
	v_add_f32_e32 v105, v106, v107
	v_addc_co_u32_e32 v117, vcc, 0, v67, vcc
	global_load_dwordx4 v[94:97], v[110:111], off
	global_load_dwordx4 v[90:93], v[110:111], off offset:1024
	global_load_dwordx4 v[86:89], v[110:111], off offset:2048
	global_load_dwordx4 v[82:85], v[110:111], off offset:3072
	s_waitcnt lgkmcnt(1)
	s_nop 1
	v_add_f32_dpp v104, v104, v104 quad_perm:[1,0,3,2] row_mask:0xf bank_mask:0xf
	s_waitcnt lgkmcnt(0)
	s_nop 1
	v_add_f32_dpp v105, v105, v105 quad_perm:[1,0,3,2] row_mask:0xf bank_mask:0xf
	global_load_dwordx4 v[78:81], v[116:117], off
	global_load_dwordx4 v[74:77], v[116:117], off offset:1024
	global_load_dwordx4 v[70:73], v[116:117], off offset:2048
	global_load_dwordx4 v[66:69], v[116:117], off offset:3072
	s_add_u32 s12, s12, 0x2000
	s_addc_u32 s13, s13, 0
	s_waitcnt lgkmcnt(1)
	s_nop 1
	v_add_f32_dpp v104, v104, v104 quad_perm:[2,3,0,1] row_mask:0xf bank_mask:0xf
	s_nop 1
	v_add_f32_dpp v105, v105, v105 quad_perm:[2,3,0,1] row_mask:0xf bank_mask:0xf
	s_cmp_eq_u32 s12, 0x1e000
	s_waitcnt lgkmcnt(1)
	s_nop 1
	v_add_f32_dpp v104, v104, v104 row_half_mirror row_mask:0xf bank_mask:0xf
	s_nop 1
	v_add_f32_dpp v105, v105, v105 row_half_mirror row_mask:0xf bank_mask:0xf
	s_waitcnt lgkmcnt(1)
	s_nop 1
	v_add_f32_dpp v104, v104, v104 row_mirror row_mask:0xf bank_mask:0xf
	s_nop 1
	v_add_f32_dpp v105, v105, v105 row_mirror row_mask:0xf bank_mask:0xf
	s_waitcnt lgkmcnt(1)
	s_waitcnt lgkmcnt(1)
	s_nop 0
	v_readlane_b32 s98, v104, 0
	v_readlane_b32 s99, v104, 16
	v_readlane_b32 s100, v104, 32
	v_readlane_b32 s101, v104, 48
	v_mov_b32_e32 v104, s98
	v_add_f32_e32 v104, s99, v104
	v_mov_b32_e32 v106, s100
	v_add_f32_e32 v106, s101, v106
	v_add_f32_e32 v104, v104, v106
	s_nop 0
	v_readlane_b32 s98, v105, 0
	v_readlane_b32 s99, v105, 16
	v_readlane_b32 s100, v105, 32
	v_readlane_b32 s101, v105, 48
	v_mov_b32_e32 v105, s98
	v_add_f32_e32 v105, s99, v105
	v_mov_b32_e32 v107, s100
	v_add_f32_e32 v107, s101, v107
	v_add_f32_e32 v105, v105, v107
	v_fmamk_f32 v35, v104, 0xba800000, v35
	v_fmamk_f32 v34, v104, 0xba800000, v34
	v_fmamk_f32 v37, v104, 0xba800000, v37
	v_fmac_f32_e32 v36, 0xba800000, v104
	v_fmamk_f32 v39, v104, 0xba800000, v39
	v_fmamk_f32 v38, v104, 0xba800000, v38
	v_fmamk_f32 v41, v104, 0xba800000, v41
	v_fmac_f32_e32 v40, 0xba800000, v104
	v_fmamk_f32 v43, v104, 0xba800000, v43
	v_fmamk_f32 v42, v104, 0xba800000, v42
	v_fmamk_f32 v45, v104, 0xba800000, v45
	v_fmac_f32_e32 v44, 0xba800000, v104
	v_fmamk_f32 v49, v104, 0xba800000, v49
	v_fmamk_f32 v48, v104, 0xba800000, v48
	v_fmamk_f32 v47, v104, 0xba800000, v47
	v_fmac_f32_e32 v46, 0xba800000, v104
	v_fmamk_f32 v51, v105, 0xba800000, v51
	v_fmamk_f32 v50, v105, 0xba800000, v50
	v_fmamk_f32 v53, v105, 0xba800000, v53
	v_fmac_f32_e32 v52, 0xba800000, v105
	v_fmamk_f32 v55, v105, 0xba800000, v55
	v_fmamk_f32 v54, v105, 0xba800000, v54
	v_fmamk_f32 v57, v105, 0xba800000, v57
	v_fmac_f32_e32 v56, 0xba800000, v105
	v_fmamk_f32 v59, v105, 0xba800000, v59
	v_fmamk_f32 v58, v105, 0xba800000, v58
	v_fmamk_f32 v61, v105, 0xba800000, v61
	v_fmac_f32_e32 v60, 0xba800000, v105
	v_fmamk_f32 v65, v105, 0xba800000, v65
	v_fmamk_f32 v64, v105, 0xba800000, v64
	v_fmamk_f32 v63, v105, 0xba800000, v63
	v_fmac_f32_e32 v62, 0xba800000, v105
	v_pk_mul_f32 v[104:105], v[36:37], v[36:37]
	v_pk_mul_f32 v[106:107], v[34:35], v[34:35]
	v_pk_mul_f32 v[110:111], v[40:41], v[40:41]
	v_pk_mul_f32 v[112:113], v[38:39], v[38:39]
	v_mul_f32_e32 v114, v42, v42
	v_mul_f32_e32 v116, v44, v44
	v_pk_mul_f32 v[118:119], v[52:53], v[52:53]
	v_pk_mul_f32 v[120:121], v[50:51], v[50:51]
	v_pk_mul_f32 v[122:123], v[56:57], v[56:57]
	v_pk_mul_f32 v[124:125], v[54:55], v[54:55]
	v_pk_mov_b32 v[130:131], v[106:107], v[104:105] op_sel:[1,0]
	v_mov_b32_e32 v107, v105
	v_pk_mov_b32 v[104:105], v[112:113], v[110:111] op_sel:[1,0]
	v_mov_b32_e32 v113, v111
	v_pk_fma_f32 v[110:111], v[42:43], v[42:43], v[114:115] op_sel_hi:[1,1,0]
; __device__ __forceinline__ unsigned pk2(float lo, float hi) { unsigned r; asm("v_cvt_pk_bf16_f32 %0, %1, %2" : "=v"(r) : "v"(lo), "v"(hi)); return r; }
; __device__ __forceinline__ void ln_panel(const float* src, float* dst, bf16_t* dstb, const float* gam, const float* bet, LAS f32x2* T) {
;     ...
;         for (int b = 0; b < NB; ++b) { const float mean = s[b] * (1.f / DM); s2[b] = 0.f;
; #pragma unroll
;             for (int j = 0; j < 4; ++j) { cur[b][j] = cur[b][j] - mean; s2[b] += (cur[b][j].x * cur[b][j].x + cur[b][j].y * cur[b][j].y) + (cur[b][j].z * cur[b][j].z + cur[b][j].w * cur[b][j].w); } }
; #pragma unroll
;         for (int o = 1; o < 64; o <<= 1)
; #pragma unroll
;             for (int b = 0; b < NB; ++b) s2[b] += __shfl_xor(s2[b], o);
; #pragma unroll
;         for (int b = 0; b < NB; ++b) {
;             const float rstd = 1.f / sqrtf(s2[b] * (1.f / DM) + LN_EPS);
;             if (T && lane == 0) T[r + b] = (f32x2){s[b] * (1.f / DM), rstd};
; #pragma unroll
;             for (int j = 0; j < 4; ++j) {
;                 const f32x4 o = cur[b][j] * rstd * gv[j] + bv[j];
;                 if (dst) ((f32x4*)(dst + (size_t)(r + b) * DM))[lane + 64 * j] = o;
;                 if (dstb) { u32x2 w; w.x = pk2(o.x, o.y); w.y = pk2(o.z, o.w); ((u32x2*)(dstb + (size_t)(r + b) * DM))[lane + 64 * j] = w; }
	v_pk_fma_f32 v[114:115], v[44:45], v[44:45], v[116:117] op_sel_hi:[1,1,0]
	v_pk_mov_b32 v[116:117], v[120:121], v[118:119] op_sel:[1,0]
	v_mov_b32_e32 v121, v119
	v_pk_mov_b32 v[118:119], v[124:125], v[122:123] op_sel:[1,0]
	v_mov_b32_e32 v125, v123
	v_pk_add_f32 v[106:107], v[130:131], v[106:107]
	v_pk_add_f32 v[104:105], v[104:105], v[112:113]
	v_mul_f32_e32 v126, v58, v58
	v_mul_f32_e32 v128, v60, v60
	v_mul_f32_e32 v110, v46, v46
	v_mul_f32_e32 v114, v47, v47
	v_pk_add_f32 v[112:113], v[116:117], v[120:121]
	v_pk_add_f32 v[116:117], v[118:119], v[124:125]
	v_pk_add_f32 v[106:107], v[106:107], v[106:107] op_sel_hi:[0,1]
	v_pk_add_f32 v[104:105], v[104:105], v[104:105] op_sel_hi:[0,1]
	v_pk_fma_f32 v[122:123], v[58:59], v[58:59], v[126:127] op_sel_hi:[1,1,0]
	v_pk_fma_f32 v[126:127], v[60:61], v[60:61], v[128:129] op_sel_hi:[1,1,0]
	v_pk_add_f32 v[110:111], v[110:111], v[114:115]
	v_pk_add_f32 v[112:113], v[112:113], v[112:113] op_sel_hi:[0,1]
	v_pk_add_f32 v[114:115], v[116:117], v[116:117] op_sel_hi:[0,1]
	v_mul_f32_e32 v106, v48, v48
	v_mul_f32_e32 v104, v49, v49
	v_mul_f32_e32 v122, v62, v62
	v_mul_f32_e32 v126, v63, v63
	v_mul_f32_e32 v112, v64, v64
	v_mul_f32_e32 v114, v65, v65
	v_pk_add_f32 v[104:105], v[106:107], v[104:105]
	v_pk_add_f32 v[116:117], v[122:123], v[126:127]
	v_pk_add_f32 v[106:107], v[112:113], v[114:115]
	v_pk_add_f32 v[104:105], v[110:111], v[104:105]
	v_pk_add_f32 v[106:107], v[116:117], v[106:107]
	v_add_f32_e32 v104, v104, v105
	v_add_f32_e32 v105, v106, v107
	s_waitcnt lgkmcnt(1)
	s_nop 1
	v_add_f32_dpp v104, v104, v104 quad_perm:[1,0,3,2] row_mask:0xf bank_mask:0xf
	s_nop 1
	v_add_f32_dpp v105, v105, v105 quad_perm:[1,0,3,2] row_mask:0xf bank_mask:0xf
	s_waitcnt lgkmcnt(1)
	s_nop 1
	v_add_f32_dpp v104, v104, v104 quad_perm:[2,3,0,1] row_mask:0xf bank_mask:0xf
	s_nop 1
	v_add_f32_dpp v105, v105, v105 quad_perm:[2,3,0,1] row_mask:0xf bank_mask:0xf
	s_waitcnt lgkmcnt(1)
	s_nop 1
	v_add_f32_dpp v104, v104, v104 row_half_mirror row_mask:0xf bank_mask:0xf
	s_nop 1
	v_add_f32_dpp v105, v105, v105 row_half_mirror row_mask:0xf bank_mask:0xf
	s_waitcnt lgkmcnt(1)
	s_nop 1
	v_add_f32_dpp v104, v104, v104 row_mirror row_mask:0xf bank_mask:0xf
	s_nop 1
	v_add_f32_dpp v105, v105, v105 row_mirror row_mask:0xf bank_mask:0xf
	s_waitcnt lgkmcnt(1)
	s_waitcnt lgkmcnt(1)
	s_nop 0
	v_readlane_b32 s98, v104, 0
	v_readlane_b32 s99, v104, 16
	v_readlane_b32 s100, v104, 32
	v_readlane_b32 s101, v104, 48
	v_mov_b32_e32 v104, s98
	v_add_f32_e32 v104, s99, v104
	v_mov_b32_e32 v106, s100
	v_add_f32_e32 v106, s101, v106
	v_add_f32_e32 v104, v104, v106
	s_nop 0
	v_readlane_b32 s98, v105, 0
	v_readlane_b32 s99, v105, 16
	v_readlane_b32 s100, v105, 32
	v_readlane_b32 s101, v105, 48
	v_mov_b32_e32 v105, s98
	v_add_f32_e32 v105, s99, v105
	v_mov_b32_e32 v107, s100
	v_add_f32_e32 v107, s101, v107
	v_add_f32_e32 v105, v105, v107
	v_fmamk_f32 v104, v104, 0x3a800000, v99
	v_fmamk_f32 v105, v105, 0x3a800000, v99
	v_mul_f32_e32 v106, 0x4f800000, v104
	v_cmp_gt_f32_e64 s[4:5], s11, v104
	v_mul_f32_e32 v107, 0x4f800000, v105
	v_cmp_gt_f32_e32 vcc, s11, v105
	v_cndmask_b32_e64 v104, v104, v106, s[4:5]
	v_sqrt_f32_e32 v106, v104
	v_cndmask_b32_e32 v105, v105, v107, vcc
	v_sqrt_f32_e32 v107, v105
	v_add_u32_e32 v109, -1, v106
	v_add_u32_e32 v110, 1, v106
	v_add_u32_e32 v111, -1, v107
	v_fma_f32 v113, -v109, v106, v104
	v_add_u32_e32 v112, 1, v107
	v_fma_f32 v114, -v110, v106, v104
	v_fma_f32 v115, -v111, v107, v105
	v_cmp_ge_f32_e64 s[6:7], 0, v113
	v_fma_f32 v116, -v112, v107, v105
	v_cmp_lt_f32_e64 s[8:9], 0, v114
	v_cndmask_b32_e64 v106, v106, v109, s[6:7]
	v_cmp_ge_f32_e64 s[6:7], 0, v115
	v_cndmask_b32_e64 v106, v106, v110, s[8:9]
	v_mul_f32_e32 v109, 0x37800000, v106
	v_cndmask_b32_e64 v107, v107, v111, s[6:7]
	v_cmp_lt_f32_e64 s[6:7], 0, v116
	v_cndmask_b32_e64 v106, v106, v109, s[4:5]
	v_cmp_class_f32_e64 s[4:5], v104, v108
	v_cndmask_b32_e64 v107, v107, v112, s[6:7]
	v_mul_f32_e32 v110, 0x37800000, v107
	v_cndmask_b32_e32 v107, v107, v110, vcc
	v_cmp_class_f32_e32 vcc, v105, v108
	v_cndmask_b32_e64 v104, v106, v104, s[4:5]
	s_nop 0
	v_cndmask_b32_e32 v109, v107, v105, vcc
	v_div_scale_f32 v105, s[4:5], v104, v104, 1.0
	v_rcp_f32_e32 v111, v105
	v_div_scale_f32 v107, s[4:5], v109, v109, 1.0
	v_rcp_f32_e32 v112, v107
	v_fma_f32 v113, -v105, v111, 1.0
	v_div_scale_f32 v106, vcc, 1.0, v104, 1.0
	v_fmac_f32_e32 v111, v113, v111
	v_fma_f32 v114, -v107, v112, 1.0
	v_mul_f32_e32 v113, v106, v111
	v_div_scale_f32 v110, s[4:5], 1.0, v109, 1.0
	v_fmac_f32_e32 v112, v114, v112
	v_fma_f32 v115, -v105, v113, v106
	v_mul_f32_e32 v114, v110, v112
	v_fmac_f32_e32 v113, v115, v111
	v_fma_f32 v116, -v107, v114, v110
	v_fma_f32 v105, -v105, v113, v106
	v_fmac_f32_e32 v114, v116, v112
	v_div_fmas_f32 v105, v105, v111, v113
	v_fma_f32 v106, -v107, v114, v110
	v_div_fixup_f32 v104, v105, v104, 1.0
	s_mov_b64 vcc, s[4:5]
	v_div_fmas_f32 v122, v106, v112, v114
	v_pk_mul_f32 v[106:107], v[34:35], v[104:105] op_sel_hi:[1,0]
	v_pk_mul_f32 v[110:111], v[36:37], v[104:105] op_sel_hi:[1,0]
	v_pk_mul_f32 v[112:113], v[38:39], v[104:105] op_sel_hi:[1,0]
	v_pk_mul_f32 v[114:115], v[40:41], v[104:105] op_sel_hi:[1,0]
	v_pk_mul_f32 v[116:117], v[42:43], v[104:105] op_sel_hi:[1,0]
	v_pk_mul_f32 v[118:119], v[44:45], v[104:105] op_sel_hi:[1,0]
	v_pk_mul_f32 v[120:121], v[46:47], v[104:105] op_sel_hi:[1,0]
	v_pk_mul_f32 v[104:105], v[48:49], v[104:105] op_sel_hi:[1,0]
	v_div_fixup_f32 v122, v122, v109, 1.0
	s_waitcnt vmcnt(13)
	v_pk_fma_f32 v[106:107], v[26:27], v[106:107], v[30:31]
	v_pk_fma_f32 v[110:111], v[28:29], v[110:111], v[32:33]
	s_waitcnt vmcnt(12)
; __device__ __forceinline__ unsigned pk2(float lo, float hi) { unsigned r; asm("v_cvt_pk_bf16_f32 %0, %1, %2" : "=v"(r) : "v"(lo), "v"(hi)); return r; }
; __device__ __forceinline__ void ln_panel(const float* src, float* dst, bf16_t* dstb, const float* gam, const float* bet, LAS f32x2* T) {
;     ...
;         for (int b = 0; b < NB; ++b) {
;             const float rstd = 1.f / sqrtf(s2[b] * (1.f / DM) + LN_EPS);
;             if (T && lane == 0) T[r + b] = (f32x2){s[b] * (1.f / DM), rstd};
; #pragma unroll
;             for (int j = 0; j < 4; ++j) {
;                 const f32x4 o = cur[b][j] * rstd * gv[j] + bv[j];
;                 if (dst) ((f32x4*)(dst + (size_t)(r + b) * DM))[lane + 64 * j] = o;
;                 if (dstb) { u32x2 w; w.x = pk2(o.x, o.y); w.y = pk2(o.z, o.w); ((u32x2*)(dstb + (size_t)(r + b) * DM))[lane + 64 * j] = w; }
;             }
;         }
; #pragma unroll
;         for (int b = 0; b < NB; ++b)
; #pragma unroll
;             for (int j = 0; j < 4; ++j) cur[b][j] = nxt[b][j];
	v_pk_fma_f32 v[114:115], v[20:21], v[114:115], v[24:25]
	v_pk_fma_f32 v[112:113], v[18:19], v[112:113], v[22:23]
	s_waitcnt vmcnt(9)
	v_pk_fma_f32 v[116:117], v[10:11], v[116:117], v[14:15]
	s_waitcnt vmcnt(8)
	v_pk_fma_f32 v[104:105], v[4:5], v[104:105], v[8:9]
	v_pk_mul_f32 v[124:125], v[50:51], v[122:123] op_sel_hi:[1,0]
	v_pk_mul_f32 v[126:127], v[52:53], v[122:123] op_sel_hi:[1,0]
	v_cvt_pk_bf16_f32 v106, v106, v107
	v_cvt_pk_bf16_f32 v107, v110, v111
	s_waitcnt vmcnt(7)
	v_mov_b64_e32 v[34:35], v[94:95]
	s_waitcnt vmcnt(6)
	v_mov_b64_e32 v[38:39], v[90:91]
	s_waitcnt vmcnt(5)
	v_mov_b64_e32 v[42:43], v[86:87]
	s_waitcnt vmcnt(4)
	v_mov_b64_e32 v[46:47], v[82:83]
	v_pk_fma_f32 v[118:119], v[12:13], v[118:119], v[16:17]
	v_pk_fma_f32 v[120:121], v[2:3], v[120:121], v[6:7]
	v_pk_mul_f32 v[128:129], v[54:55], v[122:123] op_sel_hi:[1,0]
	v_pk_mul_f32 v[130:131], v[56:57], v[122:123] op_sel_hi:[1,0]
	v_pk_mul_f32 v[132:133], v[58:59], v[122:123] op_sel_hi:[1,0]
	v_pk_mul_f32 v[134:135], v[60:61], v[122:123] op_sel_hi:[1,0]
	v_pk_mul_f32 v[136:137], v[62:63], v[122:123] op_sel_hi:[1,0]
	v_pk_mul_f32 v[122:123], v[64:65], v[122:123] op_sel_hi:[1,0]
	s_waitcnt vmcnt(3)
	v_mov_b64_e32 v[50:51], v[78:79]
	s_waitcnt vmcnt(2)
	v_mov_b64_e32 v[54:55], v[74:75]
	s_waitcnt vmcnt(1)
	v_mov_b64_e32 v[58:59], v[70:71]
	s_waitcnt vmcnt(0)
	v_mov_b64_e32 v[62:63], v[66:67]
	v_cvt_pk_bf16_f32 v110, v112, v113
	v_cvt_pk_bf16_f32 v111, v114, v115
	v_cvt_pk_bf16_f32 v112, v116, v117
	v_cvt_pk_bf16_f32 v113, v118, v119
	v_cvt_pk_bf16_f32 v114, v120, v121
	v_cvt_pk_bf16_f32 v115, v104, v105
	v_pk_fma_f32 v[104:105], v[28:29], v[126:127], v[32:33]
	v_pk_fma_f32 v[116:117], v[26:27], v[124:125], v[30:31]
	global_store_dwordx2 v[100:101], v[106:107], off offset:-2048
	global_store_dwordx2 v[100:101], v[110:111], off offset:-1536
	global_store_dwordx2 v[100:101], v[112:113], off offset:-1024
	global_store_dwordx2 v[100:101], v[114:115], off offset:-512
	v_cvt_pk_bf16_f32 v106, v116, v117
	v_cvt_pk_bf16_f32 v107, v104, v105
	v_mov_b64_e32 v[36:37], v[96:97]
	v_mov_b64_e32 v[40:41], v[92:93]
	v_mov_b64_e32 v[44:45], v[88:89]
	v_mov_b64_e32 v[48:49], v[84:85]
	v_mov_b64_e32 v[52:53], v[80:81]
	v_mov_b64_e32 v[56:57], v[76:77]
	v_mov_b64_e32 v[60:61], v[72:73]
	v_mov_b64_e32 v[64:65], v[68:69]
	v_pk_fma_f32 v[118:119], v[20:21], v[130:131], v[24:25]
	v_pk_fma_f32 v[120:121], v[18:19], v[128:129], v[22:23]
	v_pk_fma_f32 v[124:125], v[12:13], v[134:135], v[16:17]
	v_pk_fma_f32 v[126:127], v[10:11], v[132:133], v[14:15]
	v_pk_fma_f32 v[122:123], v[4:5], v[122:123], v[8:9]
	v_pk_fma_f32 v[128:129], v[2:3], v[136:137], v[6:7]
	v_cvt_pk_bf16_f32 v104, v120, v121
	v_cvt_pk_bf16_f32 v105, v118, v119
	v_cvt_pk_bf16_f32 v110, v126, v127
	v_cvt_pk_bf16_f32 v111, v124, v125
	v_cvt_pk_bf16_f32 v113, v122, v123
	s_nop 0
	v_cvt_pk_bf16_f32 v112, v128, v129
	global_store_dwordx2 v[100:101], v[106:107], off
	global_store_dwordx2 v[100:101], v[104:105], off offset:512
	global_store_dwordx2 v[100:101], v[110:111], off offset:1024
	global_store_dwordx2 v[100:101], v[112:113], off offset:1536
	v_lshl_add_u64 v[100:101], v[100:101], 0, s[14:15]
	s_cbranch_scc0 .LBB0_107
	v_mov_b32_e32 v34, v95
	v_mov_b32_e32 v35, v96
	v_mov_b32_e32 v36, v94
	v_mov_b32_e32 v37, v97
	v_pk_add_f32 v[34:35], v[34:35], v[36:37]
	v_mov_b32_e32 v36, v91
	v_mov_b32_e32 v37, v92
	v_mov_b32_e32 v38, v90
	v_mov_b32_e32 v39, v93
	v_pk_add_f32 v[36:37], v[36:37], v[38:39]
	v_add_f32_e32 v34, v34, v35
	v_pk_add_f32 v[36:37], v[36:37], v[36:37] op_sel:[0,1] op_sel_hi:[1,0]
	v_add_f32_e32 v34, 0, v34
	v_add_f32_e32 v38, v86, v87
	v_add_f32_e32 v40, v88, v89
	v_mov_b32_e32 v35, v82
	v_mov_b32_e32 v37, v83
	v_mov_b32_e32 v39, v84
	v_mov_b32_e32 v41, v85
	v_pk_add_f32 v[34:35], v[34:35], v[36:37]
	v_pk_add_f32 v[36:37], v[38:39], v[40:41]
	v_mov_b32_e32 v38, v74
	v_pk_add_f32 v[34:35], v[34:35], v[36:37]
	v_mov_b32_e32 v36, v78
	v_add_f32_e32 v42, v34, v35
	v_mov_b32_e32 v34, v79
	v_mov_b32_e32 v35, v80
	v_mov_b32_e32 v37, v81
	v_pk_add_f32 v[34:35], v[34:35], v[36:37]
	v_mov_b32_e32 v36, v75
	v_mov_b32_e32 v37, v76
	v_mov_b32_e32 v39, v77
	v_pk_add_f32 v[36:37], v[36:37], v[38:39]
	v_add_f32_e32 v34, v34, v35
	v_pk_add_f32 v[36:37], v[36:37], v[36:37] op_sel:[0,1] op_sel_hi:[1,0]
	v_add_f32_e32 v34, 0, v34
	v_add_f32_e32 v38, v70, v71
	v_add_f32_e32 v40, v72, v73
	v_mov_b32_e32 v35, v66
	v_mov_b32_e32 v37, v67
	v_mov_b32_e32 v39, v68
	v_mov_b32_e32 v41, v69
	v_pk_add_f32 v[34:35], v[34:35], v[36:37]
	v_pk_add_f32 v[36:37], v[38:39], v[40:41]
	s_mov_b32 s11, 0xf800000
	v_pk_add_f32 v[34:35], v[34:35], v[36:37]
	v_readlane_b32 s4, v249, 4
	v_add_f32_e32 v34, v34, v35
	v_readlane_b32 s5, v249, 5
	s_lshl_b64 s[6:7], s[4:5], 1
	s_add_u32 s4, s24, s6
	s_waitcnt lgkmcnt(1)
	s_nop 1
	v_add_f32_dpp v35, v42, v42 quad_perm:[1,0,3,2] row_mask:0xf bank_mask:0xf
	s_waitcnt lgkmcnt(0)
	s_nop 1
	v_add_f32_dpp v34, v34, v34 quad_perm:[1,0,3,2] row_mask:0xf bank_mask:0xf
	v_writelane_b32 v249, s6, 8
	s_addc_u32 s5, s25, s7
	s_add_u32 s8, s4, 0x6000000
	s_waitcnt lgkmcnt(1)
	s_nop 1
	v_add_f32_dpp v35, v35, v35 quad_perm:[2,3,0,1] row_mask:0xf bank_mask:0xf
	s_waitcnt lgkmcnt(1)
	s_nop 1
	v_add_f32_dpp v34, v34, v34 quad_perm:[2,3,0,1] row_mask:0xf bank_mask:0xf
	s_addc_u32 s9, s5, 0
	v_writelane_b32 v249, s7, 9
	s_waitcnt lgkmcnt(1)
	s_nop 1
	v_add_f32_dpp v35, v35, v35 row_half_mirror row_mask:0xf bank_mask:0xf
	s_waitcnt lgkmcnt(1)
	s_nop 1
	v_add_f32_dpp v34, v34, v34 row_half_mirror row_mask:0xf bank_mask:0xf
	s_or_b32 s6, s10, 30
	s_ashr_i32 s7, s6, 31
	s_waitcnt lgkmcnt(1)
	s_nop 1
	v_add_f32_dpp v35, v35, v35 row_mirror row_mask:0xf bank_mask:0xf
	s_waitcnt lgkmcnt(1)
; __device__ __forceinline__ void ln_panel(const float* src, float* dst, bf16_t* dstb, const float* gam, const float* bet, LAS f32x2* T) {
;     ...
;         float s[NB], s2[NB];
; #pragma unroll
;         for (int b = 0; b < NB; ++b) { s[b] = 0.f;
; #pragma unroll
;             for (int j = 0; j < 4; ++j) s[b] += (cur[b][j].x + cur[b][j].y) + (cur[b][j].z + cur[b][j].w); }
; #pragma unroll
;         for (int o = 1; o < 64; o <<= 1)
; #pragma unroll
;             for (int b = 0; b < NB; ++b) s[b] += __shfl_xor(s[b], o);
; #pragma unroll
;         for (int b = 0; b < NB; ++b) { const float mean = s[b] * (1.f / DM); s2[b] = 0.f;
; #pragma unroll
;             for (int j = 0; j < 4; ++j) { cur[b][j] = cur[b][j] - mean; s2[b] += (cur[b][j].x * cur[b][j].x + cur[b][j].y * cur[b][j].y) + (cur[b][j].z * cur[b][j].z + cur[b][j].w * cur[b][j].w); } }
; #pragma unroll
;         for (int o = 1; o < 64; o <<= 1)
; #pragma unroll
;             for (int b = 0; b < NB; ++b) s2[b] += __shfl_xor(s2[b], o);
; #pragma unroll
;         for (int b = 0; b < NB; ++b) {
;             const float rstd = 1.f / sqrtf(s2[b] * (1.f / DM) + LN_EPS);
	s_nop 1
	v_add_f32_dpp v34, v34, v34 row_mirror row_mask:0xf bank_mask:0xf
	s_waitcnt lgkmcnt(1)
	s_waitcnt lgkmcnt(1)
	s_waitcnt lgkmcnt(1)
	s_nop 0
	v_readlane_b32 s98, v35, 0
	v_readlane_b32 s99, v35, 16
	v_readlane_b32 s100, v35, 32
	v_readlane_b32 s101, v35, 48
	v_mov_b32_e32 v50, s98
	v_add_f32_e32 v50, s99, v50
	v_mov_b32_e32 v36, s100
	v_add_f32_e32 v36, s101, v36
	v_add_f32_e32 v50, v50, v36
	v_fmamk_f32 v43, v50, 0xba800000, v95
	v_fmamk_f32 v42, v50, 0xba800000, v94
	v_fmamk_f32 v97, v50, 0xba800000, v97
	v_fmac_f32_e32 v96, 0xba800000, v50
	s_waitcnt lgkmcnt(0)
	s_nop 0
	v_readlane_b32 s98, v34, 0
	v_readlane_b32 s99, v34, 16
	v_readlane_b32 s100, v34, 32
	v_readlane_b32 s101, v34, 48
	v_mov_b32_e32 v58, s98
	v_add_f32_e32 v58, s99, v58
	v_mov_b32_e32 v37, s100
	v_add_f32_e32 v37, s101, v37
	v_add_f32_e32 v58, v58, v37
	v_pk_mul_f32 v[34:35], v[96:97], v[96:97]
	v_pk_mul_f32 v[36:37], v[42:43], v[42:43]
	v_fmamk_f32 v45, v50, 0xba800000, v91
	v_pk_mov_b32 v[38:39], v[36:37], v[34:35] op_sel:[1,0]
	v_mov_b32_e32 v37, v35
	v_pk_add_f32 v[34:35], v[38:39], v[36:37]
	v_fmamk_f32 v44, v50, 0xba800000, v90
	v_fmamk_f32 v93, v50, 0xba800000, v93
	v_fmac_f32_e32 v92, 0xba800000, v50
	v_pk_add_f32 v[34:35], v[34:35], v[34:35] op_sel_hi:[0,1]
	v_pk_mul_f32 v[36:37], v[92:93], v[92:93]
	v_pk_mul_f32 v[38:39], v[44:45], v[44:45]
	v_fmamk_f32 v46, v50, 0xba800000, v86
	v_pk_mov_b32 v[40:41], v[38:39], v[36:37] op_sel:[1,0]
	v_mov_b32_e32 v39, v37
	v_fmamk_f32 v47, v50, 0xba800000, v87
	v_fmac_f32_e32 v88, 0xba800000, v50
	v_mul_f32_e32 v34, v46, v46
	v_pk_add_f32 v[36:37], v[40:41], v[38:39]
	v_fmamk_f32 v89, v50, 0xba800000, v89
	v_pk_fma_f32 v[38:39], v[46:47], v[46:47], v[34:35] op_sel_hi:[1,1,0]
	v_mul_f32_e32 v34, v88, v88
	v_pk_add_f32 v[36:37], v[36:37], v[36:37] op_sel_hi:[0,1]
	v_pk_fma_f32 v[40:41], v[88:89], v[88:89], v[34:35] op_sel_hi:[1,1,0]
	v_fmamk_f32 v49, v50, 0xba800000, v85
	v_fmamk_f32 v48, v50, 0xba800000, v84
	v_fmamk_f32 v83, v50, 0xba800000, v83
	v_fmac_f32_e32 v82, 0xba800000, v50
	v_mul_f32_e32 v38, v82, v82
	v_mul_f32_e32 v40, v83, v83
	v_mul_f32_e32 v34, v48, v48
	v_mul_f32_e32 v36, v49, v49
	v_pk_add_f32 v[38:39], v[38:39], v[40:41]
	v_pk_add_f32 v[34:35], v[34:35], v[36:37]
	v_fmamk_f32 v81, v58, 0xba800000, v81
	v_pk_add_f32 v[34:35], v[38:39], v[34:35]
	v_fmac_f32_e32 v80, 0xba800000, v58
	v_add_f32_e32 v59, v34, v35
	v_fmamk_f32 v35, v58, 0xba800000, v79
	v_fmamk_f32 v34, v58, 0xba800000, v78
	v_pk_mul_f32 v[36:37], v[80:81], v[80:81]
	v_pk_mul_f32 v[38:39], v[34:35], v[34:35]
	v_fmamk_f32 v77, v58, 0xba800000, v77
	v_pk_mov_b32 v[40:41], v[38:39], v[36:37] op_sel:[1,0]
	v_mov_b32_e32 v39, v37
	v_pk_add_f32 v[36:37], v[40:41], v[38:39]
	v_fmamk_f32 v39, v58, 0xba800000, v75
	v_fmamk_f32 v38, v58, 0xba800000, v74
	v_fmac_f32_e32 v76, 0xba800000, v58
	v_pk_add_f32 v[50:51], v[36:37], v[36:37] op_sel_hi:[0,1]
	v_pk_mul_f32 v[36:37], v[76:77], v[76:77]
	v_pk_mul_f32 v[40:41], v[38:39], v[38:39]
	v_fmac_f32_e32 v72, 0xba800000, v58
	v_pk_mov_b32 v[52:53], v[40:41], v[36:37] op_sel:[1,0]
	v_mov_b32_e32 v41, v37
	v_pk_add_f32 v[36:37], v[52:53], v[40:41]
	v_fmamk_f32 v40, v58, 0xba800000, v70
	v_pk_add_f32 v[52:53], v[36:37], v[36:37] op_sel_hi:[0,1]
	v_fmamk_f32 v41, v58, 0xba800000, v71
	v_mul_f32_e32 v36, v40, v40
	v_fmamk_f32 v73, v58, 0xba800000, v73
	v_pk_fma_f32 v[54:55], v[40:41], v[40:41], v[36:37] op_sel_hi:[1,1,0]
	v_mul_f32_e32 v36, v72, v72
	v_pk_fma_f32 v[56:57], v[72:73], v[72:73], v[36:37] op_sel_hi:[1,1,0]
	v_fmamk_f32 v37, v58, 0xba800000, v69
	v_fmamk_f32 v36, v58, 0xba800000, v68
	v_fmamk_f32 v67, v58, 0xba800000, v67
	v_fmac_f32_e32 v66, 0xba800000, v58
	v_mul_f32_e32 v54, v66, v66
	v_mul_f32_e32 v56, v67, v67
	v_mul_f32_e32 v50, v36, v36
	v_mul_f32_e32 v52, v37, v37
	v_pk_add_f32 v[54:55], v[54:55], v[56:57]
	v_pk_add_f32 v[50:51], v[50:51], v[52:53]
	s_nop 0
	v_pk_add_f32 v[50:51], v[54:55], v[50:51]
	s_nop 0
	v_add_f32_e32 v50, v50, v51
	s_waitcnt lgkmcnt(0)
	s_nop 1
	v_add_f32_dpp v51, v59, v59 quad_perm:[1,0,3,2] row_mask:0xf bank_mask:0xf
	s_waitcnt lgkmcnt(1)
	s_nop 1
	v_add_f32_dpp v50, v50, v50 quad_perm:[1,0,3,2] row_mask:0xf bank_mask:0xf
	s_waitcnt lgkmcnt(0)
	s_nop 1
	v_add_f32_dpp v51, v51, v51 quad_perm:[2,3,0,1] row_mask:0xf bank_mask:0xf
	s_waitcnt lgkmcnt(1)
	s_nop 1
	v_add_f32_dpp v50, v50, v50 quad_perm:[2,3,0,1] row_mask:0xf bank_mask:0xf
	s_waitcnt lgkmcnt(0)
	s_nop 1
	v_add_f32_dpp v51, v51, v51 row_half_mirror row_mask:0xf bank_mask:0xf
	s_waitcnt lgkmcnt(1)
	s_nop 1
	v_add_f32_dpp v50, v50, v50 row_half_mirror row_mask:0xf bank_mask:0xf
	s_waitcnt lgkmcnt(0)
	s_nop 1
	v_add_f32_dpp v51, v51, v51 row_mirror row_mask:0xf bank_mask:0xf
	s_waitcnt lgkmcnt(1)
	s_nop 1
	v_add_f32_dpp v50, v50, v50 row_mirror row_mask:0xf bank_mask:0xf
	s_waitcnt lgkmcnt(0)
	s_waitcnt lgkmcnt(1)
	v_mov_b32_e32 v52, v50
	s_waitcnt lgkmcnt(0)
	s_nop 0
	v_readlane_b32 s98, v51, 0
	v_readlane_b32 s99, v51, 16
	v_readlane_b32 s100, v51, 32
	v_readlane_b32 s101, v51, 48
	v_mov_b32_e32 v50, s98
	v_add_f32_e32 v50, s99, v50
	v_mov_b32_e32 v53, s100
	v_add_f32_e32 v53, s101, v53
	v_add_f32_e32 v50, v50, v53
	v_mov_b32_e32 v51, 0x3727c5ac
	v_fmamk_f32 v50, v50, 0x3a800000, v51
	v_mul_f32_e32 v53, 0x4f800000, v50
	v_cmp_gt_f32_e32 vcc, s11, v50
	s_waitcnt lgkmcnt(0)
; __device__ __forceinline__ unsigned pk2(float lo, float hi) { unsigned r; asm("v_cvt_pk_bf16_f32 %0, %1, %2" : "=v"(r) : "v"(lo), "v"(hi)); return r; }
; __device__ __forceinline__ void ln_panel(const float* src, float* dst, bf16_t* dstb, const float* gam, const float* bet, LAS f32x2* T) {
;     ...
;         for (int b = 0; b < NB; ++b) {
;             const float rstd = 1.f / sqrtf(s2[b] * (1.f / DM) + LN_EPS);
;             if (T && lane == 0) T[r + b] = (f32x2){s[b] * (1.f / DM), rstd};
; #pragma unroll
;             for (int j = 0; j < 4; ++j) {
;                 const f32x4 o = cur[b][j] * rstd * gv[j] + bv[j];
;                 if (dst) ((f32x4*)(dst + (size_t)(r + b) * DM))[lane + 64 * j] = o;
;                 if (dstb) { u32x2 w; w.x = pk2(o.x, o.y); w.y = pk2(o.z, o.w); ((u32x2*)(dstb + (size_t)(r + b) * DM))[lane + 64 * j] = w; }
;             }
; __global__ void __launch_bounds__(512, 2) fwd_megakernel(Args a) {
;     ...
;     grid.sync();
	s_nop 0
	v_readlane_b32 s98, v52, 0
	v_readlane_b32 s99, v52, 16
	v_readlane_b32 s100, v52, 32
	v_readlane_b32 s101, v52, 48
	v_mov_b32_e32 v54, s98
	v_add_f32_e32 v54, s99, v54
	v_add_f32_e32 v54, s100, v54
	v_add_f32_e32 v54, s101, v54
	v_cndmask_b32_e32 v50, v50, v53, vcc
	v_sqrt_f32_e32 v53, v50
	s_nop 0
	v_add_u32_e32 v55, -1, v53
	v_fma_f32 v56, -v55, v53, v50
	v_cmp_ge_f32_e64 s[4:5], 0, v56
	v_add_u32_e32 v56, 1, v53
	s_nop 0
	v_cndmask_b32_e64 v55, v53, v55, s[4:5]
	v_fma_f32 v53, -v56, v53, v50
	v_cmp_lt_f32_e64 s[4:5], 0, v53
	s_nop 1
	v_cndmask_b32_e64 v53, v55, v56, s[4:5]
	v_mul_f32_e32 v55, 0x37800000, v53
	v_cndmask_b32_e32 v53, v53, v55, vcc
	v_mov_b32_e32 v55, 0x260
	v_cmp_class_f32_e32 vcc, v50, v55
	s_nop 1
	v_cndmask_b32_e32 v50, v53, v50, vcc
	v_div_scale_f32 v53, s[4:5], v50, v50, 1.0
	v_rcp_f32_e32 v56, v53
	s_lshl_b64 s[4:5], s[6:7], 11
	s_add_u32 s6, s8, s4
	s_addc_u32 s7, s9, s5
	v_fma_f32 v57, -v53, v56, 1.0
	v_fmac_f32_e32 v56, v57, v56
	v_div_scale_f32 v57, vcc, 1.0, v50, 1.0
	v_mul_f32_e32 v58, v57, v56
	v_fma_f32 v59, -v53, v58, v57
	v_fmac_f32_e32 v58, v59, v56
	v_fma_f32 v53, -v53, v58, v57
	v_div_fmas_f32 v53, v53, v56, v58
	v_div_fixup_f32 v50, v53, v50, 1.0
	v_pk_mul_f32 v[42:43], v[42:43], v[50:51] op_sel_hi:[1,0]
	v_pk_mul_f32 v[52:53], v[96:97], v[50:51] op_sel_hi:[1,0]
	v_pk_fma_f32 v[42:43], v[26:27], v[42:43], v[30:31]
	v_pk_fma_f32 v[52:53], v[28:29], v[52:53], v[32:33]
	v_cvt_pk_bf16_f32 v42, v42, v43
	s_nop 0
	v_cvt_pk_bf16_f32 v43, v52, v53
	v_lshlrev_b32_e32 v52, 3, v98
	global_store_dwordx2 v52, v[42:43], s[6:7]
	v_pk_mul_f32 v[42:43], v[44:45], v[50:51] op_sel_hi:[1,0]
	v_pk_mul_f32 v[44:45], v[92:93], v[50:51] op_sel_hi:[1,0]
	v_pk_fma_f32 v[42:43], v[18:19], v[42:43], v[22:23]
	v_pk_fma_f32 v[44:45], v[20:21], v[44:45], v[24:25]
	v_cvt_pk_bf16_f32 v42, v42, v43
	s_nop 0
	v_cvt_pk_bf16_f32 v43, v44, v45
	global_store_dwordx2 v52, v[42:43], s[6:7] offset:512
	v_pk_mul_f32 v[42:43], v[46:47], v[50:51] op_sel_hi:[1,0]
	v_pk_mul_f32 v[44:45], v[88:89], v[50:51] op_sel_hi:[1,0]
	v_pk_fma_f32 v[42:43], v[10:11], v[42:43], v[14:15]
	v_pk_fma_f32 v[44:45], v[12:13], v[44:45], v[16:17]
	v_cvt_pk_bf16_f32 v42, v42, v43
	s_nop 0
	v_cvt_pk_bf16_f32 v43, v44, v45
	global_store_dwordx2 v52, v[42:43], s[6:7] offset:1024
	v_pk_mul_f32 v[42:43], v[82:83], v[50:51] op_sel_hi:[1,0]
	v_fmac_f32_e32 v51, 0x3a800000, v54
	v_mul_f32_e32 v44, 0x4f800000, v51
	v_cmp_gt_f32_e32 vcc, s11, v51
	v_pk_fma_f32 v[42:43], v[2:3], v[42:43], v[6:7]
	s_nop 0
	v_cndmask_b32_e32 v46, v51, v44, vcc
	v_sqrt_f32_e32 v47, v46
	v_pk_mul_f32 v[44:45], v[48:49], v[50:51] op_sel_hi:[1,0]
	v_cvt_pk_bf16_f32 v42, v42, v43
	v_add_u32_e32 v48, -1, v47
	v_fma_f32 v49, -v48, v47, v46
	v_cmp_ge_f32_e64 s[4:5], 0, v49
	v_add_u32_e32 v49, 1, v47
	v_pk_fma_f32 v[44:45], v[4:5], v[44:45], v[8:9]
	v_cndmask_b32_e64 v48, v47, v48, s[4:5]
	v_fma_f32 v47, -v49, v47, v46
	v_cmp_lt_f32_e64 s[4:5], 0, v47
	v_cvt_pk_bf16_f32 v43, v44, v45
	global_store_dwordx2 v52, v[42:43], s[6:7] offset:1536
	s_nop 0
	v_cndmask_b32_e64 v47, v48, v49, s[4:5]
	v_mul_f32_e32 v48, 0x37800000, v47
	v_cndmask_b32_e32 v47, v47, v48, vcc
	v_cmp_class_f32_e32 vcc, v46, v55
	s_nop 1
	v_cndmask_b32_e32 v46, v47, v46, vcc
	v_div_scale_f32 v47, s[4:5], v46, v46, 1.0
	v_rcp_f32_e32 v48, v47
	s_or_b32 s4, s1, 31
	s_ashr_i32 s5, s4, 31
	s_lshl_b64 s[4:5], s[4:5], 11
	v_fma_f32 v42, -v47, v48, 1.0
	v_fmac_f32_e32 v48, v42, v48
	v_div_scale_f32 v42, vcc, 1.0, v46, 1.0
	v_mul_f32_e32 v43, v42, v48
	v_fma_f32 v44, -v47, v43, v42
	v_fmac_f32_e32 v43, v44, v48
	v_fma_f32 v42, -v47, v43, v42
	v_div_fmas_f32 v42, v42, v48, v43
	v_div_fixup_f32 v42, v42, v46, 1.0
	v_pk_mul_f32 v[34:35], v[34:35], v[42:43] op_sel_hi:[1,0]
	s_add_u32 s4, s8, s4
	v_pk_mul_f32 v[44:45], v[80:81], v[42:43] op_sel_hi:[1,0]
	v_pk_fma_f32 v[26:27], v[26:27], v[34:35], v[30:31]
	s_addc_u32 s5, s9, s5
	v_pk_fma_f32 v[28:29], v[28:29], v[44:45], v[32:33]
	v_cvt_pk_bf16_f32 v26, v26, v27
	s_movk_i32 s1, 0x3ff
	v_cvt_pk_bf16_f32 v27, v28, v29
	global_store_dwordx2 v52, v[26:27], s[4:5]
	v_pk_mul_f32 v[26:27], v[38:39], v[42:43] op_sel_hi:[1,0]
	v_pk_mul_f32 v[28:29], v[76:77], v[42:43] op_sel_hi:[1,0]
	v_pk_fma_f32 v[18:19], v[18:19], v[26:27], v[22:23]
	v_pk_fma_f32 v[20:21], v[20:21], v[28:29], v[24:25]
	v_cvt_pk_bf16_f32 v18, v18, v19
	s_nop 0
	v_cvt_pk_bf16_f32 v19, v20, v21
	global_store_dwordx2 v52, v[18:19], s[4:5] offset:512
	v_pk_mul_f32 v[18:19], v[40:41], v[42:43] op_sel_hi:[1,0]
	v_pk_mul_f32 v[20:21], v[72:73], v[42:43] op_sel_hi:[1,0]
	v_pk_fma_f32 v[10:11], v[10:11], v[18:19], v[14:15]
	v_pk_fma_f32 v[12:13], v[12:13], v[20:21], v[16:17]
	v_cvt_pk_bf16_f32 v10, v10, v11
	s_nop 0
	v_cvt_pk_bf16_f32 v11, v12, v13
	global_store_dwordx2 v52, v[10:11], s[4:5] offset:1024
	v_pk_mul_f32 v[10:11], v[66:67], v[42:43] op_sel_hi:[1,0]
	v_pk_mul_f32 v[12:13], v[36:37], v[42:43] op_sel_hi:[1,0]
	v_pk_fma_f32 v[2:3], v[2:3], v[10:11], v[6:7]
	v_pk_fma_f32 v[4:5], v[4:5], v[12:13], v[8:9]
	v_cvt_pk_bf16_f32 v2, v2, v3
	s_nop 0
	v_cvt_pk_bf16_f32 v3, v4, v5
	global_store_dwordx2 v52, v[2:3], s[4:5] offset:1536
	v_lshrrev_b32_e32 v2, 20, v0
	v_lshrrev_b32_e32 v0, 10, v0
	v_or_b32_e32 v0, v0, v2
	v_and_or_b32 v0, v0, s1, v189
	v_cmp_eq_u32_e32 vcc, 0, v0
	s_barrier
	s_and_saveexec_b64 s[4:5], vcc
	s_cbranch_execz .LBB0_118
	buffer_wbl2 sc1
	s_waitcnt vmcnt(0)
	s_load_dwordx2 s[6:7], s[22:23], 0x58
	v_mov_b32_e32 v3, 0
	s_mov_b64 s[8:9], exec
	v_mbcnt_lo_u32_b32 v2, s8, 0
	v_mbcnt_hi_u32_b32 v2, s9, v2
	s_waitcnt lgkmcnt(0)
	global_load_dword v0, v3, s[6:7] offset:40
	v_cmp_eq_u32_e32 vcc, 0, v2
	s_and_saveexec_b64 s[10:11], vcc
	s_cbranch_execz .LBB0_111
	s_bcnt1_i32_b64 s1, s[8:9]
	v_mov_b32_e32 v4, s1
	global_atomic_add v4, v3, v4, s[6:7] offset:32 sc0

; __device__ __forceinline__ unsigned pk2(float lo, float hi) { unsigned r; asm("v_cvt_pk_bf16_f32 %0, %1, %2" : "=v"(r) : "v"(lo), "v"(hi)); return r; }
; __device__ __forceinline__ void ln_panel_b(bf16_t* hb, float* outf, const float* gam, const float* bet) {
;     ...
;     for (int it = 0; it < 32 / NB; ++it) {
;         const int r = r0 + it * NB;
;         float v[NB][16];
; #pragma unroll
;         for (int b = 0; b < NB; ++b)
; #pragma unroll
;             for (int j = 0; j < 2; ++j)
; #pragma unroll
;                 for (int k = 0; k < 4; ++k) { v[b][8 * j + 2 * k] = bflo(nxt[b][j][k]); v[b][8 * j + 2 * k + 1] = bfhi(nxt[b][j][k]); }
;         if (it + 1 < 32 / NB) {
; #pragma unroll
;             for (int b = 0; b < NB; ++b)
; #pragma unroll
;                 for (int j = 0; j < 2; ++j) nxt[b][j] = ((const u32x4*)(hb + (size_t)(r + NB + b) * DM))[lane + 64 * j];
;         }
;         float s[NB], s2[NB];
; #pragma unroll
;         for (int b = 0; b < NB; ++b) { s[b] = 0.f;
; #pragma unroll
;             for (int k = 0; k < 16; ++k) s[b] += v[b][k]; }
; #pragma unroll
;         for (int o = 1; o < 64; o <<= 1)
; #pragma unroll
;             for (int b = 0; b < NB; ++b) s[b] += __shfl_xor(s[b], o);
; #pragma unroll
;         for (int b = 0; b < NB; ++b) { const float mean = s[b] * (1.f / DM); s2[b] = 0.f;
; #pragma unroll
;             for (int k = 0; k < 16; ++k) { v[b][k] -= mean; s2[b] += v[b][k] * v[b][k]; } }
; #pragma unroll
;         for (int o = 1; o < 64; o <<= 1)
; #pragma unroll
;             for (int b = 0; b < NB; ++b) s2[b] += __shfl_xor(s2[b], o);
; #pragma unroll
;         for (int b = 0; b < NB; ++b) {
;             const float rstd = 1.f / sqrtf(s2[b] * (1.f / DM) + LN_EPS);
; #pragma unroll
;             for (int j = 0; j < 2; ++j) {
;                 float o[8];
; #pragma unroll
;                 for (int k = 0; k < 8; ++k) o[k] = v[b][8 * j + k] * rstd * gv[j][k >> 2][k & 3] + bv[j][k >> 2][k & 3];
;                 if (outf) { f32x4* op = (f32x4*)(outf + (size_t)(r + b) * DM + 512 * j + 8 * lane); op[0] = (f32x4){o[0], o[1], o[2], o[3]}; op[1] = (f32x4){o[4], o[5], o[6], o[7]}; }
;                 else { u32x4 w; w.x = pk2(o[0], o[1]); w.y = pk2(o[2], o[3]); w.z = pk2(o[4], o[5]); w.w = pk2(o[6], o[7]); ((u32x4*)(hb + (size_t)(r + b) * DM))[lane + 64 * j] = w; }
;             }
;         }
;     }
.LBB0_425:
	s_waitcnt vmcnt(4)
	v_lshlrev_b32_e32 v0, 16, v34
	v_and_b32_e32 v51, 0xffff0000, v34
	v_add_f32_e32 v86, 0, v0
	v_lshlrev_b32_e32 v56, 16, v35
	v_add_f32_e32 v86, v86, v51
	v_and_b32_e32 v57, 0xffff0000, v35
	v_add_f32_e32 v86, v86, v56
	v_lshlrev_b32_e32 v58, 16, v36
	v_add_f32_e32 v86, v86, v57
	v_and_b32_e32 v59, 0xffff0000, v36
	v_lshlrev_b32_e32 v70, 16, v42
	v_add_f32_e32 v86, v86, v58
	v_lshlrev_b32_e32 v60, 16, v37
	v_and_b32_e32 v71, 0xffff0000, v42
	v_add_f32_e32 v86, v86, v59
	v_add_f32_e32 v87, 0, v70
	v_and_b32_e32 v61, 0xffff0000, v37
	v_lshlrev_b32_e32 v72, 16, v43
	v_add_f32_e32 v86, v86, v60
	v_add_f32_e32 v87, v87, v71
	v_lshlrev_b32_e32 v62, 16, v38
	v_and_b32_e32 v73, 0xffff0000, v43
	v_add_f32_e32 v86, v86, v61
	v_add_f32_e32 v87, v87, v72
	v_and_b32_e32 v63, 0xffff0000, v38
	v_lshlrev_b32_e32 v74, 16, v44
	v_add_f32_e32 v86, v86, v62
	v_add_f32_e32 v87, v87, v73
	v_lshlrev_b32_e32 v64, 16, v39
	v_and_b32_e32 v75, 0xffff0000, v44
	v_add_f32_e32 v86, v86, v63
	v_add_f32_e32 v87, v87, v74
	v_and_b32_e32 v65, 0xffff0000, v39
	v_lshlrev_b32_e32 v76, 16, v45
	v_add_f32_e32 v86, v86, v64
	v_add_f32_e32 v87, v87, v75
	v_lshlrev_b32_e32 v66, 16, v40
	v_and_b32_e32 v77, 0xffff0000, v45
	v_add_f32_e32 v86, v86, v65
	v_add_f32_e32 v87, v87, v76
	v_and_b32_e32 v67, 0xffff0000, v40
	v_lshlrev_b32_e32 v78, 16, v46
	v_add_f32_e32 v86, v86, v66
	v_add_f32_e32 v87, v87, v77
	v_lshlrev_b32_e32 v68, 16, v41
	v_and_b32_e32 v79, 0xffff0000, v46
	v_add_f32_e32 v86, v86, v67
	v_add_f32_e32 v87, v87, v78
	v_and_b32_e32 v69, 0xffff0000, v41
	v_lshlrev_b32_e32 v80, 16, v47
	v_add_f32_e32 v86, v86, v68
	v_add_f32_e32 v87, v87, v79
	v_and_b32_e32 v81, 0xffff0000, v47
	v_add_f32_e32 v86, v86, v69
	v_add_f32_e32 v87, v87, v80
	v_lshlrev_b32_e32 v82, 16, v48
	v_add_f32_e32 v87, v87, v81
	v_and_b32_e32 v83, 0xffff0000, v48
	v_add_f32_e32 v87, v87, v82
	v_lshlrev_b32_e32 v84, 16, v49
	v_add_f32_e32 v87, v87, v83
	v_and_b32_e32 v85, 0xffff0000, v49
	v_add_f32_e32 v87, v87, v84
	v_add_f32_e32 v87, v87, v85
	s_waitcnt lgkmcnt(0)
	s_nop 1
	v_add_f32_dpp v86, v86, v86 quad_perm:[1,0,3,2] row_mask:0xf bank_mask:0xf
	v_lshl_add_u64 v[54:55], v[52:53], 0, s[26:27]
	s_mov_b32 s1, 0x6001000
	v_add_co_u32_e32 v46, vcc, s1, v54
	s_nop 1
	v_add_f32_dpp v87, v87, v87 quad_perm:[1,0,3,2] row_mask:0xf bank_mask:0xf
	v_addc_co_u32_e32 v47, vcc, 0, v55, vcc
	global_load_dwordx4 v[34:37], v[46:47], off
	global_load_dwordx4 v[38:41], v[46:47], off offset:1024
	global_load_dwordx4 v[42:45], v[46:47], off offset:2048
	s_nop 0
	global_load_dwordx4 v[46:49], v[46:47], off offset:3072
	s_mov_b32 s1, 0x6000000
	s_nop 1
	v_add_f32_dpp v86, v86, v86 quad_perm:[2,3,0,1] row_mask:0xf bank_mask:0xf
	s_add_u32 s26, s26, 0x1000
	s_addc_u32 s27, s27, 0
	s_cmpk_lg_u32 s26, 0xf000
	s_nop 1
	v_add_f32_dpp v87, v87, v87 quad_perm:[2,3,0,1] row_mask:0xf bank_mask:0xf
	s_nop 1
	v_add_f32_dpp v86, v86, v86 row_half_mirror row_mask:0xf bank_mask:0xf
	s_nop 1
	v_add_f32_dpp v87, v87, v87 row_half_mirror row_mask:0xf bank_mask:0xf
	s_nop 1
	v_add_f32_dpp v86, v86, v86 row_mirror row_mask:0xf bank_mask:0xf
	s_nop 1
	v_add_f32_dpp v87, v87, v87 row_mirror row_mask:0xf bank_mask:0xf
	s_nop 0
	v_readlane_b32 s98, v86, 0
	v_readlane_b32 s99, v86, 16
	v_readlane_b32 s100, v86, 32
	v_readlane_b32 s101, v86, 48
	v_mov_b32_e32 v86, s98
	v_add_f32_e32 v86, s99, v86
	v_mov_b32_e32 v88, s100
	v_add_f32_e32 v88, s101, v88
	v_add_f32_e32 v86, v86, v88
	v_fmac_f32_e32 v51, 0xba800000, v86
	v_fmac_f32_e32 v0, 0xba800000, v86
	v_fmac_f32_e32 v56, 0xba800000, v86
	v_fmac_f32_e32 v57, 0xba800000, v86
	s_nop 0
	v_readlane_b32 s98, v87, 0
	v_readlane_b32 s99, v87, 16
	v_readlane_b32 s100, v87, 32
	v_readlane_b32 s101, v87, 48
	v_mov_b32_e32 v87, s98
	v_add_f32_e32 v87, s99, v87
	v_mov_b32_e32 v88, s100
	v_add_f32_e32 v88, s101, v88
	v_add_f32_e32 v87, v87, v88
	v_mul_f32_e32 v88, v51, v51
	v_fmac_f32_e32 v88, v0, v0
	v_fmac_f32_e32 v88, v56, v56
	v_fmac_f32_e32 v88, v57, v57
	v_fmac_f32_e32 v58, 0xba800000, v86
	v_fmac_f32_e32 v88, v58, v58
	v_fmac_f32_e32 v59, 0xba800000, v86
	v_fmac_f32_e32 v71, 0xba800000, v87
	v_fmac_f32_e32 v88, v59, v59
	v_fmac_f32_e32 v60, 0xba800000, v86
	v_fmac_f32_e32 v61, 0xba800000, v86
	v_fmac_f32_e32 v62, 0xba800000, v86
	v_fmac_f32_e32 v63, 0xba800000, v86
	v_fmac_f32_e32 v64, 0xba800000, v86
	v_fmac_f32_e32 v65, 0xba800000, v86
	v_fmac_f32_e32 v66, 0xba800000, v86
	v_fmac_f32_e32 v67, 0xba800000, v86
	v_fmac_f32_e32 v68, 0xba800000, v86
	v_fmac_f32_e32 v69, 0xba800000, v86
	v_fmac_f32_e32 v70, 0xba800000, v87
	v_mul_f32_e32 v86, v71, v71
	v_fmac_f32_e32 v88, v60, v60
	v_fmac_f32_e32 v86, v70, v70
	v_fmac_f32_e32 v72, 0xba800000, v87
	v_fmac_f32_e32 v88, v61, v61
	v_fmac_f32_e32 v86, v72, v72
	v_fmac_f32_e32 v73, 0xba800000, v87
	v_fmac_f32_e32 v88, v62, v62
	v_fmac_f32_e32 v86, v73, v73
	v_fmac_f32_e32 v74, 0xba800000, v87
	v_fmac_f32_e32 v88, v63, v63
	v_fmac_f32_e32 v86, v74, v74
	v_fmac_f32_e32 v75, 0xba800000, v87
	v_fmac_f32_e32 v88, v64, v64
	v_fmac_f32_e32 v86, v75, v75
	v_fmac_f32_e32 v76, 0xba800000, v87
	v_fmac_f32_e32 v88, v65, v65
	v_fmac_f32_e32 v86, v76, v76
	v_fmac_f32_e32 v77, 0xba800000, v87
	v_fmac_f32_e32 v88, v66, v66
	v_fmac_f32_e32 v86, v77, v77
	v_fmac_f32_e32 v78, 0xba800000, v87
	v_fmac_f32_e32 v88, v67, v67
	v_fmac_f32_e32 v86, v78, v78
	v_fmac_f32_e32 v79, 0xba800000, v87
	v_fmac_f32_e32 v88, v68, v68
	v_fmac_f32_e32 v86, v79, v79
	v_fmac_f32_e32 v80, 0xba800000, v87
	v_fmac_f32_e32 v88, v69, v69
	v_fmac_f32_e32 v86, v80, v80
	v_fmac_f32_e32 v81, 0xba800000, v87
	v_fmac_f32_e32 v86, v81, v81
	v_fmac_f32_e32 v82, 0xba800000, v87
; __device__ __forceinline__ unsigned pk2(float lo, float hi) { unsigned r; asm("v_cvt_pk_bf16_f32 %0, %1, %2" : "=v"(r) : "v"(lo), "v"(hi)); return r; }
; __device__ __forceinline__ void ln_panel_b(bf16_t* hb, float* outf, const float* gam, const float* bet) {
;     ...
;         for (int b = 0; b < NB; ++b) { const float mean = s[b] * (1.f / DM); s2[b] = 0.f;
; #pragma unroll
;             for (int k = 0; k < 16; ++k) { v[b][k] -= mean; s2[b] += v[b][k] * v[b][k]; } }
; #pragma unroll
;         for (int o = 1; o < 64; o <<= 1)
; #pragma unroll
;             for (int b = 0; b < NB; ++b) s2[b] += __shfl_xor(s2[b], o);
; #pragma unroll
;         for (int b = 0; b < NB; ++b) {
;             const float rstd = 1.f / sqrtf(s2[b] * (1.f / DM) + LN_EPS);
; #pragma unroll
;             for (int j = 0; j < 2; ++j) {
;                 float o[8];
; #pragma unroll
;                 for (int k = 0; k < 8; ++k) o[k] = v[b][8 * j + k] * rstd * gv[j][k >> 2][k & 3] + bv[j][k >> 2][k & 3];
;                 if (outf) { f32x4* op = (f32x4*)(outf + (size_t)(r + b) * DM + 512 * j + 8 * lane); op[0] = (f32x4){o[0], o[1], o[2], o[3]}; op[1] = (f32x4){o[4], o[5], o[6], o[7]}; }
;                 else { u32x4 w; w.x = pk2(o[0], o[1]); w.y = pk2(o[2], o[3]); w.z = pk2(o[4], o[5]); w.w = pk2(o[6], o[7]); ((u32x4*)(hb + (size_t)(r + b) * DM))[lane + 64 * j] = w; }
;             }
	v_fmac_f32_e32 v83, 0xba800000, v87
	v_fmac_f32_e32 v84, 0xba800000, v87
	v_fmac_f32_e32 v85, 0xba800000, v87
	v_fmac_f32_e32 v86, v82, v82
	v_fmac_f32_e32 v86, v83, v83
	v_fmac_f32_e32 v86, v84, v84
	v_fmac_f32_e32 v86, v85, v85
	s_nop 1
	v_add_f32_dpp v87, v88, v88 quad_perm:[1,0,3,2] row_mask:0xf bank_mask:0xf
	s_nop 1
	v_add_f32_dpp v86, v86, v86 quad_perm:[1,0,3,2] row_mask:0xf bank_mask:0xf
	s_nop 1
	v_add_f32_dpp v87, v87, v87 quad_perm:[2,3,0,1] row_mask:0xf bank_mask:0xf
	s_nop 1
	v_add_f32_dpp v86, v86, v86 quad_perm:[2,3,0,1] row_mask:0xf bank_mask:0xf
	s_nop 1
	v_add_f32_dpp v87, v87, v87 row_half_mirror row_mask:0xf bank_mask:0xf
	s_nop 1
	v_add_f32_dpp v86, v86, v86 row_half_mirror row_mask:0xf bank_mask:0xf
	s_nop 1
	v_add_f32_dpp v87, v87, v87 row_mirror row_mask:0xf bank_mask:0xf
	s_nop 1
	v_add_f32_dpp v86, v86, v86 row_mirror row_mask:0xf bank_mask:0xf
	s_nop 0
	v_readlane_b32 s98, v87, 0
	v_readlane_b32 s99, v87, 16
	v_readlane_b32 s100, v87, 32
	v_readlane_b32 s101, v87, 48
	v_mov_b32_e32 v87, s98
	v_add_f32_e32 v87, s99, v87
	v_mov_b32_e32 v88, s100
	v_add_f32_e32 v88, s101, v88
	v_add_f32_e32 v87, v87, v88
	v_fmamk_f32 v87, v87, 0x3a800000, v231
	v_cmp_gt_f32_e32 vcc, s97, v87
	s_nop 0
	v_readlane_b32 s98, v86, 0
	v_readlane_b32 s99, v86, 16
	v_readlane_b32 s100, v86, 32
	v_readlane_b32 s101, v86, 48
	v_mov_b32_e32 v86, s98
	v_add_f32_e32 v86, s99, v86
	v_mov_b32_e32 v88, s100
	v_add_f32_e32 v88, s101, v88
	v_add_f32_e32 v86, v86, v88
	v_mul_f32_e32 v88, 0x4f800000, v87
	v_cndmask_b32_e32 v87, v87, v88, vcc
	v_sqrt_f32_e32 v88, v87
	s_nop 0
	v_add_u32_e32 v89, -1, v88
	v_fma_f32 v90, -v89, v88, v87
	v_cmp_ge_f32_e64 s[2:3], 0, v90
	v_add_u32_e32 v90, 1, v88
	s_nop 0
	v_cndmask_b32_e64 v89, v88, v89, s[2:3]
	v_fma_f32 v88, -v90, v88, v87
	v_cmp_lt_f32_e64 s[2:3], 0, v88
	s_nop 1
	v_cndmask_b32_e64 v88, v89, v90, s[2:3]
	v_mul_f32_e32 v89, 0x37800000, v88
	v_cndmask_b32_e32 v88, v88, v89, vcc
	v_cmp_class_f32_e32 vcc, v87, v232
	s_nop 1
	v_cndmask_b32_e32 v87, v88, v87, vcc
	v_div_scale_f32 v88, s[2:3], v87, v87, 1.0
	v_rcp_f32_e32 v89, v88
	s_nop 0
	v_fma_f32 v90, -v88, v89, 1.0
	v_fmac_f32_e32 v89, v90, v89
	v_div_scale_f32 v90, vcc, 1.0, v87, 1.0
	v_mul_f32_e32 v91, v90, v89
	v_fma_f32 v92, -v88, v91, v90
	v_fmac_f32_e32 v91, v92, v89
	v_fma_f32 v88, -v88, v91, v90
	v_div_fmas_f32 v88, v88, v89, v91
	v_div_fixup_f32 v87, v88, v87, 1.0
	v_mul_f32_e32 v56, v56, v87
	v_fma_f32 v88, v32, v56, v24
	v_mul_f32_e32 v56, v57, v87
	v_fma_f32 v57, v33, v56, v25
	v_mul_f32_e32 v56, v58, v87
	v_fma_f32 v58, v26, v56, v18
	v_mul_f32_e32 v56, v59, v87
	v_fma_f32 v59, v27, v56, v19
	v_mul_f32_e32 v56, v60, v87
	v_fma_f32 v60, v28, v56, v20
	v_mul_f32_e32 v56, v61, v87
	v_mul_f32_e32 v0, v0, v87
	v_mul_f32_e32 v51, v51, v87
	v_fma_f32 v61, v29, v56, v21
	v_cvt_pk_bf16_f32 v58, v58, v59
	v_cvt_pk_bf16_f32 v59, v60, v61
	v_add_co_u32_e32 v60, vcc, s1, v54
	v_mul_f32_e32 v54, v64, v87
	v_fma_f32 v0, v30, v0, v22
	v_fma_f32 v51, v31, v51, v23
	v_cvt_pk_bf16_f32 v56, v0, v51
	v_addc_co_u32_e32 v61, vcc, 0, v55, vcc
	v_fma_f32 v55, v16, v54, v8
	v_mul_f32_e32 v54, v65, v87
	v_cvt_pk_bf16_f32 v57, v88, v57
	global_store_dwordx4 v[60:61], v[56:59], off
	v_mul_f32_e32 v0, v62, v87
	v_fma_f32 v0, v14, v0, v6
	v_fma_f32 v56, v17, v54, v9
	v_mul_f32_e32 v54, v66, v87
	v_fma_f32 v57, v10, v54, v2
	v_mul_f32_e32 v54, v67, v87
	v_fma_f32 v58, v11, v54, v3
	v_mul_f32_e32 v54, v68, v87
	v_mul_f32_e32 v51, v63, v87
	v_fma_f32 v59, v12, v54, v4
	v_mul_f32_e32 v54, v69, v87
	v_fma_f32 v51, v15, v51, v7
	v_fma_f32 v62, v13, v54, v5
	v_cvt_pk_bf16_f32 v54, v0, v51
	v_fmamk_f32 v0, v86, 0x3a800000, v231
	v_cmp_gt_f32_e32 vcc, s97, v0
	v_mul_f32_e32 v51, 0x4f800000, v0
	v_cvt_pk_bf16_f32 v55, v55, v56
	v_cvt_pk_bf16_f32 v56, v57, v58
	v_cvt_pk_bf16_f32 v57, v59, v62
	global_store_dwordx4 v[60:61], v[54:57], off offset:1024
	v_cndmask_b32_e32 v0, v0, v51, vcc
	v_sqrt_f32_e32 v51, v0
	s_nop 0
	v_add_u32_e32 v54, -1, v51
	v_fma_f32 v55, -v54, v51, v0
	v_cmp_ge_f32_e64 s[2:3], 0, v55
	v_add_u32_e32 v55, 1, v51
	s_nop 0
	v_cndmask_b32_e64 v54, v51, v54, s[2:3]
	v_fma_f32 v51, -v55, v51, v0
	v_cmp_lt_f32_e64 s[2:3], 0, v51
	s_nop 1
	v_cndmask_b32_e64 v51, v54, v55, s[2:3]
	v_mul_f32_e32 v54, 0x37800000, v51
	v_cndmask_b32_e32 v51, v51, v54, vcc
	v_cmp_class_f32_e32 vcc, v0, v232
	s_nop 1
	v_cndmask_b32_e32 v0, v51, v0, vcc
	v_div_scale_f32 v51, s[2:3], v0, v0, 1.0
	v_rcp_f32_e32 v54, v51
	s_nop 0
	v_fma_f32 v55, -v51, v54, 1.0
	v_fmac_f32_e32 v54, v55, v54
	v_div_scale_f32 v55, vcc, 1.0, v0, 1.0
	v_mul_f32_e32 v56, v55, v54
	v_fma_f32 v57, -v51, v56, v55
	v_fmac_f32_e32 v56, v57, v54
	v_fma_f32 v51, -v51, v56, v55
	v_div_fmas_f32 v51, v51, v54, v56
	v_div_fixup_f32 v0, v51, v0, 1.0
	v_mul_f32_e32 v54, v71, v0
	v_mul_f32_e32 v55, v72, v0
	v_mul_f32_e32 v56, v73, v0
	v_mul_f32_e32 v57, v74, v0
	v_mul_f32_e32 v51, v70, v0
	v_fma_f32 v54, v31, v54, v23
	v_fma_f32 v55, v32, v55, v24
	v_fma_f32 v56, v33, v56, v25
	v_fma_f32 v57, v26, v57, v18
	v_mul_f32_e32 v58, v75, v0
	v_mul_f32_e32 v59, v76, v0
	v_mul_f32_e32 v62, v77, v0
	v_fma_f32 v51, v30, v51, v22
	v_fma_f32 v58, v27, v58, v19
	v_fma_f32 v59, v28, v59, v20
	v_fma_f32 v62, v29, v62, v21
	v_cvt_pk_bf16_f32 v54, v51, v54
	v_cvt_pk_bf16_f32 v55, v55, v56
	v_cvt_pk_bf16_f32 v56, v57, v58
	v_cvt_pk_bf16_f32 v57, v59, v62
	global_store_dwordx4 v[60:61], v[54:57], off offset:2048
	v_mul_f32_e32 v51, v78, v0
	v_mul_f32_e32 v58, v83, v0
	v_mul_f32_e32 v54, v79, v0
	v_mul_f32_e32 v55, v80, v0
	v_mul_f32_e32 v56, v81, v0
	v_mul_f32_e32 v57, v82, v0
	v_fma_f32 v54, v15, v54, v7
	v_fma_f32 v55, v16, v55, v8
	v_fma_f32 v56, v17, v56, v9
	v_fma_f32 v57, v10, v57, v2
	v_mul_f32_e32 v59, v84, v0
	v_mul_f32_e32 v0, v85, v0
	v_fma_f32 v51, v14, v51, v6
	v_fma_f32 v58, v11, v58, v3
	v_fma_f32 v59, v12, v59, v4
	v_fma_f32 v0, v13, v0, v5
	v_cvt_pk_bf16_f32 v54, v51, v54
	v_cvt_pk_bf16_f32 v55, v55, v56
	v_cvt_pk_bf16_f32 v56, v57, v58
	v_cvt_pk_bf16_f32 v57, v59, v0
	global_store_dwordx4 v[60:61], v[54:57], off offset:3072
	s_cbranch_scc1 .LBB0_425
; __device__ __forceinline__ float bflo(unsigned w) { return __uint_as_float(w << 16); }
; __device__ __forceinline__ float bfhi(unsigned w) { return __uint_as_float(w & 0xffff0000u); }
; __device__ __forceinline__ void ln_panel_b(bf16_t* hb, float* outf, const float* gam, const float* bet) {
;     ...
;         for (int b = 0; b < NB; ++b)
; #pragma unroll
;             for (int j = 0; j < 2; ++j)
; #pragma unroll
;                 for (int k = 0; k < 4; ++k) { v[b][8 * j + 2 * k] = bflo(nxt[b][j][k]); v[b][8 * j + 2 * k + 1] = bfhi(nxt[b][j][k]); }
;         if (it + 1 < 32 / NB) {
; #pragma unroll
;             for (int b = 0; b < NB; ++b)
; #pragma unroll
;                 for (int j = 0; j < 2; ++j) nxt[b][j] = ((const u32x4*)(hb + (size_t)(r + NB + b) * DM))[lane + 64 * j];
;         }
;         float s[NB], s2[NB];
; #pragma unroll
;         for (int b = 0; b < NB; ++b) { s[b] = 0.f;
; #pragma unroll
;             for (int k = 0; k < 16; ++k) s[b] += v[b][k]; }
; #pragma unroll
;         for (int o = 1; o < 64; o <<= 1)
; #pragma unroll
;             for (int b = 0; b < NB; ++b) s[b] += __shfl_xor(s[b], o);
; #pragma unroll
;         for (int b = 0; b < NB; ++b) { const float mean = s[b] * (1.f / DM); s2[b] = 0.f;
; #pragma unroll
;             for (int k = 0; k < 16; ++k) { v[b][k] -= mean; s2[b] += v[b][k] * v[b][k]; } }
	s_waitcnt vmcnt(7)
	v_and_b32_e32 v65, 0xffff0000, v34
	v_lshlrev_b32_e32 v34, 16, v34
	v_add_f32_e32 v66, 0, v34
	v_and_b32_e32 v64, 0xffff0000, v35
	v_lshlrev_b32_e32 v35, 16, v35
	v_add_f32_e32 v66, v66, v65
	v_add_f32_e32 v66, v66, v35
	v_and_b32_e32 v63, 0xffff0000, v36
	v_lshlrev_b32_e32 v36, 16, v36
	v_add_f32_e32 v66, v66, v64
	s_waitcnt vmcnt(5)
	v_and_b32_e32 v57, 0xffff0000, v42
	v_lshlrev_b32_e32 v42, 16, v42
	v_add_f32_e32 v66, v66, v36
	v_and_b32_e32 v62, 0xffff0000, v37
	v_lshlrev_b32_e32 v37, 16, v37
	v_add_f32_e32 v66, v66, v63
	v_add_f32_e32 v67, 0, v42
	v_and_b32_e32 v56, 0xffff0000, v43
	v_lshlrev_b32_e32 v43, 16, v43
	v_add_f32_e32 v66, v66, v37
	v_add_f32_e32 v67, v67, v57
	v_and_b32_e32 v61, 0xffff0000, v38
	v_lshlrev_b32_e32 v38, 16, v38
	v_add_f32_e32 v66, v66, v62
	v_add_f32_e32 v67, v67, v43
	v_and_b32_e32 v55, 0xffff0000, v44
	v_lshlrev_b32_e32 v44, 16, v44
	v_add_f32_e32 v66, v66, v38
	v_add_f32_e32 v67, v67, v56
	v_and_b32_e32 v60, 0xffff0000, v39
	v_lshlrev_b32_e32 v39, 16, v39
	v_add_f32_e32 v66, v66, v61
	v_add_f32_e32 v67, v67, v44
	v_and_b32_e32 v54, 0xffff0000, v45
	v_lshlrev_b32_e32 v45, 16, v45
	v_add_f32_e32 v66, v66, v39
	v_add_f32_e32 v67, v67, v55
	v_and_b32_e32 v59, 0xffff0000, v40
	v_lshlrev_b32_e32 v40, 16, v40
	v_add_f32_e32 v66, v66, v60
	v_add_f32_e32 v67, v67, v45
	s_waitcnt vmcnt(4)
	v_and_b32_e32 v53, 0xffff0000, v46
	v_lshlrev_b32_e32 v46, 16, v46
	v_add_f32_e32 v66, v66, v40
	v_add_f32_e32 v67, v67, v54
	v_and_b32_e32 v58, 0xffff0000, v41
	v_lshlrev_b32_e32 v41, 16, v41
	v_add_f32_e32 v66, v66, v59
	v_add_f32_e32 v67, v67, v46
	v_and_b32_e32 v52, 0xffff0000, v47
	v_lshlrev_b32_e32 v47, 16, v47
	v_add_f32_e32 v66, v66, v41
	v_add_f32_e32 v67, v67, v53
	v_add_f32_e32 v66, v66, v58
	v_add_f32_e32 v67, v67, v47
	v_and_b32_e32 v51, 0xffff0000, v48
	v_lshlrev_b32_e32 v48, 16, v48
	v_add_f32_e32 v67, v67, v52
	v_add_f32_e32 v67, v67, v48
	v_and_b32_e32 v0, 0xffff0000, v49
	v_lshlrev_b32_e32 v49, 16, v49
	v_add_f32_e32 v67, v67, v51
	v_add_f32_e32 v67, v67, v49
	v_add_f32_e32 v67, v67, v0
	s_waitcnt lgkmcnt(0)
	s_nop 1
	v_add_f32_dpp v66, v66, v66 quad_perm:[1,0,3,2] row_mask:0xf bank_mask:0xf
	s_or_b32 s10, s10, 30
	s_ashr_i32 s11, s10, 31
	v_lshlrev_b32_e32 v50, 4, v50
	s_movk_i32 s42, 0x400
	s_waitcnt lgkmcnt(0)
	s_nop 1
	v_add_f32_dpp v67, v67, v67 quad_perm:[1,0,3,2] row_mask:0xf bank_mask:0xf
	v_mov_b32_e32 v131, v1
	v_mov_b32_e32 v135, v1
	v_mov_b32_e32 v133, v1
	s_waitcnt lgkmcnt(0)
	s_nop 1
	v_add_f32_dpp v66, v66, v66 quad_perm:[2,3,0,1] row_mask:0xf bank_mask:0xf
	s_waitcnt lgkmcnt(0)
	s_nop 1
	v_add_f32_dpp v67, v67, v67 quad_perm:[2,3,0,1] row_mask:0xf bank_mask:0xf
	s_waitcnt lgkmcnt(0)
	s_nop 1
	v_add_f32_dpp v66, v66, v66 row_half_mirror row_mask:0xf bank_mask:0xf
	s_waitcnt lgkmcnt(0)
	s_nop 1
	v_add_f32_dpp v67, v67, v67 row_half_mirror row_mask:0xf bank_mask:0xf
	s_waitcnt lgkmcnt(0)
	s_nop 1
	v_add_f32_dpp v66, v66, v66 row_mirror row_mask:0xf bank_mask:0xf
	s_waitcnt lgkmcnt(0)
	s_nop 1
	v_add_f32_dpp v67, v67, v67 row_mirror row_mask:0xf bank_mask:0xf
	s_waitcnt lgkmcnt(0)
	s_waitcnt lgkmcnt(0)
	s_waitcnt lgkmcnt(0)
	s_nop 0
	v_readlane_b32 s98, v66, 0
	v_readlane_b32 s99, v66, 16
	v_readlane_b32 s100, v66, 32
	v_readlane_b32 s101, v66, 48
	v_mov_b32_e32 v66, s98
	v_add_f32_e32 v66, s99, v66
	v_mov_b32_e32 v68, s100
	v_add_f32_e32 v68, s101, v68
	v_add_f32_e32 v66, v66, v68
	v_fmac_f32_e32 v65, 0xba800000, v66
	v_fmac_f32_e32 v34, 0xba800000, v66
	v_fmac_f32_e32 v35, 0xba800000, v66
	v_fmac_f32_e32 v64, 0xba800000, v66
	s_waitcnt lgkmcnt(0)
	s_nop 0
	v_readlane_b32 s98, v67, 0
	v_readlane_b32 s99, v67, 16
	v_readlane_b32 s100, v67, 32
	v_readlane_b32 s101, v67, 48
	v_mov_b32_e32 v67, s98
	v_add_f32_e32 v67, s99, v67
	v_mov_b32_e32 v68, s100
	v_add_f32_e32 v68, s101, v68
	v_add_f32_e32 v67, v67, v68
	v_mul_f32_e32 v68, v65, v65
	v_fmac_f32_e32 v68, v34, v34
	v_fmac_f32_e32 v68, v35, v35
	v_fmac_f32_e32 v68, v64, v64
	v_fmac_f32_e32 v36, 0xba800000, v66
	v_fmac_f32_e32 v68, v36, v36
	v_fmac_f32_e32 v63, 0xba800000, v66
	v_fmac_f32_e32 v57, 0xba800000, v67
	v_fmac_f32_e32 v68, v63, v63
	v_fmac_f32_e32 v37, 0xba800000, v66
	v_fmac_f32_e32 v62, 0xba800000, v66
	v_fmac_f32_e32 v38, 0xba800000, v66
	v_fmac_f32_e32 v61, 0xba800000, v66
	v_fmac_f32_e32 v39, 0xba800000, v66
	v_fmac_f32_e32 v60, 0xba800000, v66
	v_fmac_f32_e32 v40, 0xba800000, v66
	v_fmac_f32_e32 v59, 0xba800000, v66
	v_fmac_f32_e32 v41, 0xba800000, v66
	v_fmac_f32_e32 v58, 0xba800000, v66
	v_fmac_f32_e32 v42, 0xba800000, v67
	v_mul_f32_e32 v66, v57, v57
	v_fmac_f32_e32 v68, v37, v37
	v_fmac_f32_e32 v66, v42, v42
	v_fmac_f32_e32 v43, 0xba800000, v67
	v_fmac_f32_e32 v68, v62, v62
	v_fmac_f32_e32 v66, v43, v43
	v_fmac_f32_e32 v56, 0xba800000, v67
	v_fmac_f32_e32 v68, v38, v38
	v_fmac_f32_e32 v66, v56, v56
	v_fmac_f32_e32 v44, 0xba800000, v67
	v_fmac_f32_e32 v68, v61, v61
	v_fmac_f32_e32 v66, v44, v44
	v_fmac_f32_e32 v55, 0xba800000, v67
	v_fmac_f32_e32 v68, v39, v39
	v_fmac_f32_e32 v66, v55, v55
	v_fmac_f32_e32 v45, 0xba800000, v67
	v_fmac_f32_e32 v68, v60, v60
	v_fmac_f32_e32 v66, v45, v45
	v_fmac_f32_e32 v54, 0xba800000, v67
	v_fmac_f32_e32 v68, v40, v40
	v_fmac_f32_e32 v66, v54, v54
	v_fmac_f32_e32 v46, 0xba800000, v67
	v_fmac_f32_e32 v68, v59, v59
	v_fmac_f32_e32 v66, v46, v46
	v_fmac_f32_e32 v53, 0xba800000, v67
	v_fmac_f32_e32 v68, v41, v41
	v_fmac_f32_e32 v66, v53, v53
	v_fmac_f32_e32 v47, 0xba800000, v67
	v_fmac_f32_e32 v68, v58, v58
	v_fmac_f32_e32 v66, v47, v47
	v_fmac_f32_e32 v52, 0xba800000, v67
	v_fmac_f32_e32 v66, v52, v52
	v_fmac_f32_e32 v48, 0xba800000, v67
	v_fmac_f32_e32 v51, 0xba800000, v67
	v_fmac_f32_e32 v49, 0xba800000, v67
	v_fmac_f32_e32 v0, 0xba800000, v67
	v_fmac_f32_e32 v66, v48, v48
	v_fmac_f32_e32 v66, v51, v51
	v_fmac_f32_e32 v66, v49, v49
	v_fmac_f32_e32 v66, v0, v0
	s_waitcnt lgkmcnt(0)
; __device__ __forceinline__ unsigned pk2(float lo, float hi) { unsigned r; asm("v_cvt_pk_bf16_f32 %0, %1, %2" : "=v"(r) : "v"(lo), "v"(hi)); return r; }
; __device__ __forceinline__ void ln_panel_b(bf16_t* hb, float* outf, const float* gam, const float* bet) {
;     ...
;         for (int o = 1; o < 64; o <<= 1)
; #pragma unroll
;             for (int b = 0; b < NB; ++b) s2[b] += __shfl_xor(s2[b], o);
; #pragma unroll
;         for (int b = 0; b < NB; ++b) {
;             const float rstd = 1.f / sqrtf(s2[b] * (1.f / DM) + LN_EPS);
; #pragma unroll
;             for (int j = 0; j < 2; ++j) {
;                 float o[8];
; #pragma unroll
;                 for (int k = 0; k < 8; ++k) o[k] = v[b][8 * j + k] * rstd * gv[j][k >> 2][k & 3] + bv[j][k >> 2][k & 3];
;                 if (outf) { f32x4* op = (f32x4*)(outf + (size_t)(r + b) * DM + 512 * j + 8 * lane); op[0] = (f32x4){o[0], o[1], o[2], o[3]}; op[1] = (f32x4){o[4], o[5], o[6], o[7]}; }
;                 else { u32x4 w; w.x = pk2(o[0], o[1]); w.y = pk2(o[2], o[3]); w.z = pk2(o[4], o[5]); w.w = pk2(o[6], o[7]); ((u32x4*)(hb + (size_t)(r + b) * DM))[lane + 64 * j] = w; }
;             }
;         }
;     }
	s_nop 1
	v_add_f32_dpp v67, v68, v68 quad_perm:[1,0,3,2] row_mask:0xf bank_mask:0xf
	s_waitcnt lgkmcnt(0)
	s_nop 1
	v_add_f32_dpp v66, v66, v66 quad_perm:[1,0,3,2] row_mask:0xf bank_mask:0xf
	s_waitcnt lgkmcnt(0)
	s_nop 1
	v_add_f32_dpp v67, v67, v67 quad_perm:[2,3,0,1] row_mask:0xf bank_mask:0xf
	s_waitcnt lgkmcnt(0)
	s_nop 1
	v_add_f32_dpp v66, v66, v66 quad_perm:[2,3,0,1] row_mask:0xf bank_mask:0xf
	s_waitcnt lgkmcnt(0)
	s_nop 1
	v_add_f32_dpp v67, v67, v67 row_half_mirror row_mask:0xf bank_mask:0xf
	s_waitcnt lgkmcnt(0)
	s_nop 1
	v_add_f32_dpp v66, v66, v66 row_half_mirror row_mask:0xf bank_mask:0xf
	s_waitcnt lgkmcnt(0)
	s_nop 1
	v_add_f32_dpp v67, v67, v67 row_mirror row_mask:0xf bank_mask:0xf
	s_waitcnt lgkmcnt(0)
	s_nop 1
	v_add_f32_dpp v66, v66, v66 row_mirror row_mask:0xf bank_mask:0xf
	s_waitcnt lgkmcnt(0)
	s_waitcnt lgkmcnt(0)
	s_waitcnt lgkmcnt(0)
	s_nop 0
	v_readlane_b32 s98, v67, 0
	v_readlane_b32 s99, v67, 16
	v_readlane_b32 s100, v67, 32
	v_readlane_b32 s101, v67, 48
	v_mov_b32_e32 v67, s98
	v_add_f32_e32 v67, s99, v67
	v_mov_b32_e32 v68, s100
	v_add_f32_e32 v68, s101, v68
	v_add_f32_e32 v67, v67, v68
	v_fmamk_f32 v67, v67, 0x3a800000, v231
	v_cmp_gt_f32_e32 vcc, s97, v67
	s_waitcnt lgkmcnt(0)
	s_nop 0
	v_readlane_b32 s98, v66, 0
	v_readlane_b32 s99, v66, 16
	v_readlane_b32 s100, v66, 32
	v_readlane_b32 s101, v66, 48
	v_mov_b32_e32 v66, s98
	v_add_f32_e32 v66, s99, v66
	v_mov_b32_e32 v68, s100
	v_add_f32_e32 v68, s101, v68
	v_add_f32_e32 v66, v66, v68
	v_mul_f32_e32 v68, 0x4f800000, v67
	v_cndmask_b32_e32 v67, v67, v68, vcc
	v_sqrt_f32_e32 v68, v67
	s_nop 0
	v_add_u32_e32 v69, -1, v68
	v_fma_f32 v70, -v69, v68, v67
	v_cmp_ge_f32_e64 s[2:3], 0, v70
	v_add_u32_e32 v70, 1, v68
	s_nop 0
	v_cndmask_b32_e64 v69, v68, v69, s[2:3]
	v_fma_f32 v68, -v70, v68, v67
	v_cmp_lt_f32_e64 s[2:3], 0, v68
	s_nop 1
	v_cndmask_b32_e64 v68, v69, v70, s[2:3]
	v_mul_f32_e32 v69, 0x37800000, v68
	v_cndmask_b32_e32 v68, v68, v69, vcc
	v_cmp_class_f32_e32 vcc, v67, v232
	s_nop 1
	v_cndmask_b32_e32 v67, v68, v67, vcc
	v_div_scale_f32 v68, s[2:3], v67, v67, 1.0
	v_rcp_f32_e32 v69, v68
	s_lshl_b64 s[2:3], s[10:11], 11
	s_add_u32 s2, s4, s2
	s_addc_u32 s3, s5, s3
	v_fma_f32 v70, -v68, v69, 1.0
	v_fmac_f32_e32 v69, v70, v69
	v_div_scale_f32 v70, vcc, 1.0, v67, 1.0
	v_mul_f32_e32 v71, v70, v69
	v_fma_f32 v72, -v68, v71, v70
	v_fmac_f32_e32 v71, v72, v69
	v_fma_f32 v68, -v68, v71, v70
	v_div_fmas_f32 v68, v68, v69, v71
	v_div_fixup_f32 v67, v68, v67, 1.0
	v_mul_f32_e32 v34, v34, v67
	v_fma_f32 v34, v30, v34, v22
	v_mul_f32_e32 v65, v65, v67
	v_mul_f32_e32 v35, v35, v67
	v_mul_f32_e32 v36, v36, v67
	v_mul_f32_e32 v37, v37, v67
	v_fma_f32 v65, v31, v65, v23
	v_fma_f32 v35, v32, v35, v24
	v_mul_f32_e32 v64, v64, v67
	v_fma_f32 v36, v26, v36, v18
	v_mul_f32_e32 v63, v63, v67
	v_fma_f32 v37, v28, v37, v20
	v_mul_f32_e32 v62, v62, v67
	v_cvt_pk_bf16_f32 v34, v34, v65
	v_fma_f32 v64, v33, v64, v25
	v_fma_f32 v63, v27, v63, v19
	v_fma_f32 v62, v29, v62, v21
	v_cvt_pk_bf16_f32 v35, v35, v64
	v_cvt_pk_bf16_f32 v36, v36, v63
	v_cvt_pk_bf16_f32 v37, v37, v62
	global_store_dwordx4 v50, v[34:37], s[2:3]
	s_nop 1
	v_mul_f32_e32 v34, v38, v67
	v_fma_f32 v34, v14, v34, v6
	v_mul_f32_e32 v35, v61, v67
	v_mul_f32_e32 v36, v39, v67
	v_mul_f32_e32 v37, v60, v67
	v_fma_f32 v35, v15, v35, v7
	v_fma_f32 v36, v16, v36, v8
	v_fma_f32 v37, v17, v37, v9
	v_mul_f32_e32 v38, v40, v67
	v_mul_f32_e32 v39, v59, v67
	v_mul_f32_e32 v40, v41, v67
	v_mul_f32_e32 v41, v58, v67
	v_cvt_pk_bf16_f32 v34, v34, v35
	v_fma_f32 v38, v10, v38, v2
	v_fma_f32 v39, v11, v39, v3
	v_fma_f32 v40, v12, v40, v4
	v_fma_f32 v41, v13, v41, v5
	v_cvt_pk_bf16_f32 v35, v36, v37
	v_cvt_pk_bf16_f32 v36, v38, v39
	v_cvt_pk_bf16_f32 v37, v40, v41
	global_store_dwordx4 v50, v[34:37], s[2:3] offset:1024
	s_nop 1
	v_fmamk_f32 v34, v66, 0x3a800000, v231
	v_cmp_gt_f32_e32 vcc, s97, v34
	v_mul_f32_e32 v35, 0x4f800000, v34
	s_nop 0
	v_cndmask_b32_e32 v34, v34, v35, vcc
	v_sqrt_f32_e32 v35, v34
	s_nop 0
	v_add_u32_e32 v36, -1, v35
	v_fma_f32 v37, -v36, v35, v34
	v_cmp_ge_f32_e64 s[2:3], 0, v37
	v_add_u32_e32 v37, 1, v35
	s_nop 0
	v_cndmask_b32_e64 v36, v35, v36, s[2:3]
	v_fma_f32 v35, -v37, v35, v34
	v_cmp_lt_f32_e64 s[2:3], 0, v35
	s_nop 1
	v_cndmask_b32_e64 v35, v36, v37, s[2:3]
	v_mul_f32_e32 v36, 0x37800000, v35
	v_cndmask_b32_e32 v35, v35, v36, vcc
	v_cmp_class_f32_e32 vcc, v34, v232
	s_nop 1
	v_cndmask_b32_e32 v34, v35, v34, vcc
	v_div_scale_f32 v35, s[2:3], v34, v34, 1.0
	v_rcp_f32_e32 v36, v35
	s_or_b32 s2, s8, 31
	s_ashr_i32 s3, s2, 31
	s_lshl_b64 s[2:3], s[2:3], 11
	v_fma_f32 v37, -v35, v36, 1.0
	v_fmac_f32_e32 v36, v37, v36
	v_div_scale_f32 v37, vcc, 1.0, v34, 1.0
	v_mul_f32_e32 v38, v37, v36
	v_fma_f32 v39, -v35, v38, v37
	v_fmac_f32_e32 v38, v39, v36
	v_fma_f32 v35, -v35, v38, v37
	v_div_fmas_f32 v35, v35, v36, v38
	v_div_fixup_f32 v34, v35, v34, 1.0
	v_mul_f32_e32 v35, v42, v34
	v_fma_f32 v22, v30, v35, v22
	v_mul_f32_e32 v30, v57, v34
	v_fma_f32 v23, v31, v30, v23
	v_mul_f32_e32 v30, v43, v34
	v_fma_f32 v24, v32, v30, v24
	v_mul_f32_e32 v30, v56, v34
	v_fmac_f32_e32 v25, v33, v30
	v_mul_f32_e32 v30, v44, v34
	v_fma_f32 v26, v26, v30, v18
	v_mul_f32_e32 v18, v55, v34
	v_fma_f32 v27, v27, v18, v19
	v_mul_f32_e32 v18, v45, v34
	s_add_u32 s2, s4, s2
	v_fma_f32 v28, v28, v18, v20
	v_mul_f32_e32 v18, v54, v34
	s_addc_u32 s3, s5, s3
	v_fmac_f32_e32 v21, v29, v18
	v_cvt_pk_bf16_f32 v18, v22, v23
	v_cvt_pk_bf16_f32 v19, v24, v25
	v_cvt_pk_bf16_f32 v20, v26, v27
	v_cvt_pk_bf16_f32 v21, v28, v21
	global_store_dwordx4 v50, v[18:21], s[2:3]
	v_mul_f32_e32 v0, v0, v34
	v_fmac_f32_e32 v5, v13, v0
	v_mul_f32_e32 v18, v46, v34
	v_fma_f32 v6, v14, v18, v6
	v_mul_f32_e32 v14, v53, v34
	v_fma_f32 v7, v15, v14, v7
	v_mul_f32_e32 v14, v47, v34
	v_fma_f32 v8, v16, v14, v8
	v_mul_f32_e32 v14, v52, v34
	v_fmac_f32_e32 v9, v17, v14
	v_mul_f32_e32 v14, v48, v34
	v_fma_f32 v10, v10, v14, v2
	v_mul_f32_e32 v2, v51, v34
	v_fma_f32 v11, v11, v2, v3
	v_mul_f32_e32 v2, v49, v34
	v_fma_f32 v12, v12, v2, v4
	v_cvt_pk_bf16_f32 v2, v6, v7
	v_cvt_pk_bf16_f32 v3, v8, v9
	v_cvt_pk_bf16_f32 v4, v10, v11
	v_cvt_pk_bf16_f32 v5, v12, v5
	global_store_dwordx4 v50, v[2:5], s[2:3] offset:1024
	v_readlane_b32 s2, v249, 0
	v_readlane_b32 s3, v249, 1
	v_mov_b32_e32 v15, v189
	s_waitcnt vmcnt(0)
	s_barrier
	v_readfirstlane_b32 s98, v189
	s_nop 3
	s_cmp_ge_u32 s98, 64
	s_cbranch_scc1 .Lgrp_bar0_done
	s_lshr_b32 s98, s88, 21
	s_and_b32 s99, s98, 7
	s_lshr_b32 s98, s98, 5
	s_lshl_b32 s98, s98, 3
	s_or_b32 s98, s98, s99
	s_lshl_b32 s98, s98, 5
	v_readlane_b32 s99, v248, 36
	s_nop 3
	s_lshl_b32 s99, s99, 4
	s_add_u32 s98, s98, s99
	s_add_u32 s98, s98, 14336
	v_mov_b32_e32 v2, s98
	v_mov_b32_e32 v3, 1
	s_mov_b64 s[100:101], exec
	s_mov_b64 exec, 1
	v_readlane_b32 s99, v248, 62
	s_nop 3
	s_cmp_eq_u32 s99, 1
	s_cbranch_scc1 .Lgrp_bar0_nowb
	buffer_wbl2 sc1

; __device__ __forceinline__ void ln_panel_b(bf16_t* hb, float* outf, const float* gam, const float* bet) {
;     ...
;         if (it + 1 < 32 / NB) {
; #pragma unroll
;             for (int b = 0; b < NB; ++b)
; #pragma unroll
;                 for (int j = 0; j < 2; ++j) nxt[b][j] = ((const u32x4*)(hb + (size_t)(r + NB + b) * DM))[lane + 64 * j];
;         }
;         float s[NB], s2[NB];
; #pragma unroll
;         for (int b = 0; b < NB; ++b) { s[b] = 0.f;
; #pragma unroll
;             for (int k = 0; k < 16; ++k) s[b] += v[b][k]; }
; #pragma unroll
;         for (int o = 1; o < 64; o <<= 1)
; #pragma unroll
;             for (int b = 0; b < NB; ++b) s[b] += __shfl_xor(s[b], o);
; #pragma unroll
;         for (int b = 0; b < NB; ++b) { const float mean = s[b] * (1.f / DM); s2[b] = 0.f;
; #pragma unroll
;             for (int k = 0; k < 16; ++k) { v[b][k] -= mean; s2[b] += v[b][k] * v[b][k]; } }
; #pragma unroll
;         for (int o = 1; o < 64; o <<= 1)
; #pragma unroll
;             for (int b = 0; b < NB; ++b) s2[b] += __shfl_xor(s2[b], o);
.LBB0_458:
	v_lshlrev_b32_e32 v76, 16, v54
	v_and_b32_e32 v77, 0xffff0000, v54
	v_add_f32_e32 v0, 0, v76
	v_add_f32_e32 v0, v0, v77
	v_lshlrev_b32_e32 v54, 16, v55
	v_and_b32_e32 v55, 0xffff0000, v55
	v_add_f32_e32 v0, v0, v54
	v_lshlrev_b32_e32 v86, 16, v64
	v_and_b32_e32 v87, 0xffff0000, v64
	v_lshlrev_b32_e32 v84, 16, v65
	v_and_b32_e32 v85, 0xffff0000, v65
	v_lshlrev_b32_e32 v90, 16, v62
	v_and_b32_e32 v91, 0xffff0000, v62
	v_lshlrev_b32_e32 v88, 16, v63
	v_and_b32_e32 v89, 0xffff0000, v63
	v_lshlrev_b32_e32 v62, 16, v60
	v_and_b32_e32 v63, 0xffff0000, v60
	v_lshlrev_b32_e32 v64, 16, v61
	v_and_b32_e32 v65, 0xffff0000, v61
	v_lshlrev_b32_e32 v60, 16, v58
	v_and_b32_e32 v61, 0xffff0000, v58
	v_lshlrev_b32_e32 v58, 16, v56
	v_add_f32_e32 v0, v0, v55
	v_lshlrev_b32_e32 v92, 16, v59
	v_and_b32_e32 v93, 0xffff0000, v59
	v_and_b32_e32 v59, 0xffff0000, v56
	v_add_f32_e32 v0, v0, v58
	v_lshlrev_b32_e32 v56, 16, v57
	v_add_f32_e32 v0, v0, v59
	v_and_b32_e32 v57, 0xffff0000, v57
	v_add_f32_e32 v0, v0, v56
	v_add_f32_e32 v0, v0, v57
	v_add_f32_e32 v0, v0, v60
	v_add_f32_e32 v0, v0, v61
	v_add_f32_e32 v0, v0, v92
	v_add_f32_e32 v0, v0, v93
	v_add_f32_e32 v0, v0, v62
	v_add_f32_e32 v0, v0, v63
	v_add_f32_e32 v0, v0, v64
	v_add_f32_e32 v0, v0, v65
	v_lshl_add_u64 v[74:75], v[70:71], 0, s[20:21]
	v_add_co_u32_e32 v42, vcc, 0x6001000, v74
	s_waitcnt lgkmcnt(0)
	s_nop 1
	v_add_f32_dpp v0, v0, v0 quad_perm:[1,0,3,2] row_mask:0xf bank_mask:0xf
	v_addc_co_u32_e32 v43, vcc, 0, v75, vcc
	global_load_dwordx4 v[34:37], v[42:43], off
	global_load_dwordx4 v[46:49], v[42:43], off offset:1024
	global_load_dwordx4 v[38:41], v[42:43], off offset:2048
	s_nop 0
	global_load_dwordx4 v[42:45], v[42:43], off offset:3072
	s_nop 1
	v_add_f32_dpp v0, v0, v0 quad_perm:[2,3,0,1] row_mask:0xf bank_mask:0xf
	s_nop 1
	v_add_f32_dpp v0, v0, v0 row_half_mirror row_mask:0xf bank_mask:0xf
	s_nop 1
	v_add_f32_dpp v0, v0, v0 row_mirror row_mask:0xf bank_mask:0xf
	s_nop 0
	v_readlane_b32 s98, v0, 0
	v_readlane_b32 s99, v0, 16
	v_readlane_b32 s100, v0, 32
	v_readlane_b32 s101, v0, 48
	v_mov_b32_e32 v0, s98
	v_add_f32_e32 v0, s99, v0
	v_mov_b32_e32 v67, s100
	v_add_f32_e32 v67, s101, v67
	v_add_f32_e32 v0, v0, v67
	v_mul_f32_e32 v0, 0x3a800000, v0
	v_pk_add_f32 v[76:77], v[76:77], v[0:1] op_sel_hi:[1,0] neg_lo:[0,1] neg_hi:[0,1]
	v_pk_add_f32 v[78:79], v[54:55], v[0:1] op_sel_hi:[1,0] neg_lo:[0,1] neg_hi:[0,1]
	v_pk_mul_f32 v[94:95], v[76:77], v[76:77]
	v_pk_mul_f32 v[54:55], v[78:79], v[78:79]
	v_pk_add_f32 v[80:81], v[58:59], v[0:1] op_sel_hi:[1,0] neg_lo:[0,1] neg_hi:[0,1]
	v_pk_add_f32 v[82:83], v[56:57], v[0:1] op_sel_hi:[1,0] neg_lo:[0,1] neg_hi:[0,1]
	v_pk_add_f32 v[58:59], v[60:61], v[0:1] op_sel_hi:[1,0] neg_lo:[0,1] neg_hi:[0,1]
	v_pk_add_f32 v[60:61], v[92:93], v[0:1] op_sel_hi:[1,0] neg_lo:[0,1] neg_hi:[0,1]
	v_pk_add_f32 v[62:63], v[62:63], v[0:1] op_sel_hi:[1,0] neg_lo:[0,1] neg_hi:[0,1]
	v_pk_add_f32 v[64:65], v[64:65], v[0:1] op_sel_hi:[1,0] neg_lo:[0,1] neg_hi:[0,1]
	v_add_f32_e32 v0, v94, v95
	v_add_f32_e32 v0, v54, v0
	v_pk_mul_f32 v[96:97], v[80:81], v[80:81]
	v_add_f32_e32 v0, v55, v0
	v_add_f32_e32 v0, v96, v0
	v_pk_mul_f32 v[56:57], v[82:83], v[82:83]
	v_add_f32_e32 v0, v97, v0
	v_add_f32_e32 v0, v56, v0
	v_pk_mul_f32 v[98:99], v[58:59], v[58:59]
	v_add_f32_e32 v0, v57, v0
	v_add_f32_e32 v0, v98, v0
	v_pk_mul_f32 v[92:93], v[60:61], v[60:61]
	v_add_f32_e32 v0, v99, v0
	v_add_f32_e32 v0, v92, v0
	v_pk_mul_f32 v[100:101], v[62:63], v[62:63]
	v_add_f32_e32 v0, v93, v0
	v_add_f32_e32 v0, v100, v0
	v_pk_mul_f32 v[102:103], v[64:65], v[64:65]
	v_add_f32_e32 v0, v101, v0
	v_add_f32_e32 v0, v102, v0
	v_add_f32_e32 v0, v103, v0
	v_lshlrev_b32_e32 v56, 16, v50
	v_and_b32_e32 v57, 0xffff0000, v50
	v_add_f32_e32 v50, 0, v56
	v_add_f32_e32 v69, v50, v57
	s_nop 1
	v_add_f32_dpp v0, v0, v0 quad_perm:[1,0,3,2] row_mask:0xf bank_mask:0xf
	v_lshlrev_b32_e32 v50, 16, v51
	v_and_b32_e32 v51, 0xffff0000, v51
	v_add_f32_e32 v69, v69, v50
	v_add_f32_e32 v69, v69, v51
	s_nop 1
	v_add_f32_dpp v0, v0, v0 quad_perm:[2,3,0,1] row_mask:0xf bank_mask:0xf
	v_and_b32_e32 v55, 0xffff0000, v52
	s_nop 1
	v_add_f32_dpp v0, v0, v0 row_half_mirror row_mask:0xf bank_mask:0xf
	s_nop 1
	v_add_f32_dpp v0, v0, v0 row_mirror row_mask:0xf bank_mask:0xf
	v_lshlrev_b32_e32 v54, 16, v52
	v_add_f32_e32 v69, v69, v54
	v_lshlrev_b32_e32 v52, 16, v53
	v_add_f32_e32 v69, v69, v55
	v_and_b32_e32 v53, 0xffff0000, v53
	v_add_f32_e32 v69, v69, v52
	v_add_f32_e32 v69, v69, v53
	v_add_f32_e32 v69, v69, v90
	v_add_f32_e32 v69, v69, v91
	v_add_f32_e32 v69, v69, v88
	v_add_f32_e32 v69, v69, v89
	v_add_f32_e32 v69, v69, v86
	v_add_f32_e32 v69, v69, v87
	v_add_f32_e32 v69, v69, v84
	v_add_f32_e32 v69, v69, v85
	s_waitcnt lgkmcnt(1)
; __device__ __forceinline__ unsigned pk2(float lo, float hi) { unsigned r; asm("v_cvt_pk_bf16_f32 %0, %1, %2" : "=v"(r) : "v"(lo), "v"(hi)); return r; }
; __device__ __forceinline__ void ln_panel_b(bf16_t* hb, float* outf, const float* gam, const float* bet) {
;     ...
;         for (int o = 1; o < 64; o <<= 1)
; #pragma unroll
;             for (int b = 0; b < NB; ++b) s[b] += __shfl_xor(s[b], o);
; #pragma unroll
;         for (int b = 0; b < NB; ++b) { const float mean = s[b] * (1.f / DM); s2[b] = 0.f;
; #pragma unroll
;             for (int k = 0; k < 16; ++k) { v[b][k] -= mean; s2[b] += v[b][k] * v[b][k]; } }
; #pragma unroll
;         for (int o = 1; o < 64; o <<= 1)
; #pragma unroll
;             for (int b = 0; b < NB; ++b) s2[b] += __shfl_xor(s2[b], o);
; #pragma unroll
;         for (int b = 0; b < NB; ++b) {
;             const float rstd = 1.f / sqrtf(s2[b] * (1.f / DM) + LN_EPS);
; #pragma unroll
;             for (int j = 0; j < 2; ++j) {
;                 float o[8];
; #pragma unroll
;                 for (int k = 0; k < 8; ++k) o[k] = v[b][8 * j + k] * rstd * gv[j][k >> 2][k & 3] + bv[j][k >> 2][k & 3];
;                 if (outf) { f32x4* op = (f32x4*)(outf + (size_t)(r + b) * DM + 512 * j + 8 * lane); op[0] = (f32x4){o[0], o[1], o[2], o[3]}; op[1] = (f32x4){o[4], o[5], o[6], o[7]}; }
;                 else { u32x4 w; w.x = pk2(o[0], o[1]); w.y = pk2(o[2], o[3]); w.z = pk2(o[4], o[5]); w.w = pk2(o[6], o[7]); ((u32x4*)(hb + (size_t)(r + b) * DM))[lane + 64 * j] = w; }
	s_nop 1
	v_add_f32_dpp v69, v69, v69 quad_perm:[1,0,3,2] row_mask:0xf bank_mask:0xf
	s_nop 1
	v_add_f32_dpp v69, v69, v69 quad_perm:[2,3,0,1] row_mask:0xf bank_mask:0xf
	s_nop 1
	v_add_f32_dpp v69, v69, v69 row_half_mirror row_mask:0xf bank_mask:0xf
	s_nop 1
	v_add_f32_dpp v69, v69, v69 row_mirror row_mask:0xf bank_mask:0xf
	s_nop 0
	v_readlane_b32 s98, v69, 0
	v_readlane_b32 s99, v69, 16
	v_readlane_b32 s100, v69, 32
	v_readlane_b32 s101, v69, 48
	v_mov_b32_e32 v69, s98
	v_add_f32_e32 v69, s99, v69
	v_mov_b32_e32 v92, s100
	v_add_f32_e32 v92, s101, v92
	v_add_f32_e32 v69, v69, v92
	v_mul_f32_e32 v92, 0x3a800000, v69
	v_pk_add_f32 v[56:57], v[56:57], v[92:93] op_sel_hi:[1,0] neg_lo:[0,1] neg_hi:[0,1]
	v_pk_add_f32 v[50:51], v[50:51], v[92:93] op_sel_hi:[1,0] neg_lo:[0,1] neg_hi:[0,1]
	v_pk_mul_f32 v[94:95], v[56:57], v[56:57]
	v_pk_mul_f32 v[96:97], v[50:51], v[50:51]
	v_add_f32_e32 v69, v94, v95
	v_pk_add_f32 v[98:99], v[54:55], v[92:93] op_sel_hi:[1,0] neg_lo:[0,1] neg_hi:[0,1]
	v_add_f32_e32 v69, v96, v69
	v_pk_mul_f32 v[54:55], v[98:99], v[98:99]
	v_add_f32_e32 v69, v97, v69
	v_pk_add_f32 v[52:53], v[52:53], v[92:93] op_sel_hi:[1,0] neg_lo:[0,1] neg_hi:[0,1]
	v_add_f32_e32 v54, v54, v69
	v_pk_mul_f32 v[100:101], v[52:53], v[52:53]
	v_add_f32_e32 v54, v55, v54
	v_pk_add_f32 v[90:91], v[90:91], v[92:93] op_sel_hi:[1,0] neg_lo:[0,1] neg_hi:[0,1]
	v_add_f32_e32 v54, v100, v54
	v_pk_mul_f32 v[102:103], v[90:91], v[90:91]
	v_add_f32_e32 v54, v101, v54
	v_pk_add_f32 v[88:89], v[88:89], v[92:93] op_sel_hi:[1,0] neg_lo:[0,1] neg_hi:[0,1]
	v_add_f32_e32 v54, v102, v54
	v_pk_mul_f32 v[104:105], v[88:89], v[88:89]
	v_add_f32_e32 v54, v103, v54
	v_pk_add_f32 v[86:87], v[86:87], v[92:93] op_sel_hi:[1,0] neg_lo:[0,1] neg_hi:[0,1]
	v_add_f32_e32 v54, v104, v54
	v_pk_mul_f32 v[106:107], v[86:87], v[86:87]
	v_add_f32_e32 v54, v105, v54
	v_pk_add_f32 v[84:85], v[84:85], v[92:93] op_sel_hi:[1,0] neg_lo:[0,1] neg_hi:[0,1]
	v_add_f32_e32 v54, v106, v54
	v_pk_mul_f32 v[92:93], v[84:85], v[84:85]
	v_add_f32_e32 v54, v107, v54
	v_add_f32_e32 v54, v92, v54
	v_add_f32_e32 v54, v93, v54
	s_nop 1
	v_add_f32_dpp v54, v54, v54 quad_perm:[1,0,3,2] row_mask:0xf bank_mask:0xf
	s_nop 1
	v_add_f32_dpp v54, v54, v54 quad_perm:[2,3,0,1] row_mask:0xf bank_mask:0xf
	s_nop 1
	v_add_f32_dpp v54, v54, v54 row_half_mirror row_mask:0xf bank_mask:0xf
	s_nop 1
	v_add_f32_dpp v54, v54, v54 row_mirror row_mask:0xf bank_mask:0xf
	s_nop 0
	v_readlane_b32 s98, v54, 0
	v_readlane_b32 s99, v54, 16
	v_readlane_b32 s100, v54, 32
	v_readlane_b32 s101, v54, 48
	v_mov_b32_e32 v54, s98
	v_add_f32_e32 v54, s99, v54
	v_mov_b32_e32 v55, s100
	v_add_f32_e32 v55, s101, v55
	v_add_f32_e32 v54, v54, v55
	v_fmamk_f32 v54, v54, 0x3a800000, v231
	v_cmp_gt_f32_e32 vcc, s97, v54
	v_mul_f32_e32 v55, 0x4f800000, v54
	s_nop 0
	v_cndmask_b32_e32 v54, v54, v55, vcc
	v_sqrt_f32_e32 v55, v54
	s_nop 0
	v_add_u32_e32 v69, -1, v55
	v_fma_f32 v92, -v69, v55, v54
	v_cmp_ge_f32_e64 s[2:3], 0, v92
	v_add_u32_e32 v92, 1, v55
	s_nop 0
	v_cndmask_b32_e64 v69, v55, v69, s[2:3]
	v_fma_f32 v55, -v92, v55, v54
	v_cmp_lt_f32_e64 s[2:3], 0, v55
	s_nop 1
	v_cndmask_b32_e64 v55, v69, v92, s[2:3]
	v_mul_f32_e32 v69, 0x37800000, v55
	v_cndmask_b32_e32 v55, v55, v69, vcc
	v_cmp_class_f32_e32 vcc, v54, v232
	s_nop 1
	v_cndmask_b32_e32 v54, v55, v54, vcc
	v_div_scale_f32 v55, s[2:3], v54, v54, 1.0
	v_rcp_f32_e32 v69, v55
	s_nop 0
	v_fma_f32 v92, -v55, v69, 1.0
	v_fmac_f32_e32 v69, v92, v69
	v_div_scale_f32 v92, vcc, 1.0, v54, 1.0
	v_mul_f32_e32 v93, v92, v69
	v_fma_f32 v94, -v55, v93, v92
	v_fmac_f32_e32 v93, v94, v69
	v_fma_f32 v55, -v55, v93, v92
	v_div_fmas_f32 v55, v55, v69, v93
	v_div_fixup_f32 v92, v55, v54, 1.0
	v_pk_mul_f32 v[50:51], v[50:51], v[92:93] op_sel_hi:[1,0]
	v_pk_mul_f32 v[54:55], v[56:57], v[92:93] op_sel_hi:[1,0]
	v_pk_fma_f32 v[56:57], v[28:29], v[50:51], v[32:33]
	v_pk_mul_f32 v[50:51], v[98:99], v[92:93] op_sel_hi:[1,0]
	v_pk_mul_f32 v[52:53], v[52:53], v[92:93] op_sel_hi:[1,0]
	v_cndmask_b32_e64 v69, 0, 1, s[26:27]
	v_pk_fma_f32 v[54:55], v[26:27], v[54:55], v[30:31]
	v_pk_fma_f32 v[50:51], v[18:19], v[50:51], v[22:23]
	v_pk_fma_f32 v[52:53], v[20:21], v[52:53], v[24:25]
	v_cmp_ne_u32_e64 s[2:3], 1, v69
	s_andn2_b64 vcc, exec, s[26:27]
	s_cbranch_vccnz .LBB0_469
	global_store_dwordx4 v[72:73], v[54:57], off offset:-4096
	global_store_dwordx4 v[72:73], v[50:53], off offset:-4080
	s_cbranch_execnz .LBB0_461
